# GDN: removed the rsqrtf denormal-range guard (cmp/scale/cndmask) around 24 v_rsq_f32 whose argument is nonnegative+1e-6 (always normal)
# speedup vs baseline: 1.0061x; 1.0039x over previous
; #define LAS __attribute__((address_space(3)))
; DI unsigned f2bf(float f) { unsigned u = __float_as_uint(f); u += 0x7FFFu + ((u >> 16) & 1u); return u >> 16; }
; DI unsigned pk2(float lo, float hi) { return f2bf(lo) | (f2bf(hi) << 16); }
; DI float bf2f(unsigned b) { return __uint_as_float(b << 16); }
; DI float siluf_(float x) { return x * __builtin_amdgcn_rcpf(1.0f + __expf(-x)); }
; DI void gdn_unit(const Params& P, bf16_t* proj, const float* gb, int b, int h, LAS unsigned char* lds) {
;     ...
;             const float glast = __expf(gc_last);
;             bf16x8 vsb[2];
; #pragma unroll
;             for (int ks = 0; ks < 2; ++ks) vsb[ks] = ldsfrag(lds + VNS_OFF + (16 * wave + fr) * 144 + (ks * 32 + fq * 8) * 2);
; #pragma unroll
;             for (int dt = 0; dt < 8; ++dt) {
;                 f32x4 a = Sacc[dt] * glast;
;                 bf16x8 kf[2];
; #pragma unroll
;                 for (int ks = 0; ks < 2; ++ks) kf[ks] = ldsfrag(lds + KT_OFF + (dt * 16 + fr) * 144 + (ks * 32 + fq * 8) * 2);
; #pragma unroll
;                 for (int ks = 0; ks < 2; ++ks) a = MFMA16(kf[ks], vsb[ks], a);
;                 Sacc[dt] = a;
;             }
;         }
;         lds_barrier();
;         {
;             bf16_t* obase = proj + (size_t)t0 * PJ1 + 3072 + h * 128 + 16 * wave;
;             const int ooffl = fq * 4 * PJ1 + fr;
; #pragma unroll
;             for (int dt = 0; dt < 8; ++dt) {
;                 u32x2 p; p.x = pk2(Sacc[dt][0], Sacc[dt][1]); p.y = pk2(Sacc[dt][2], Sacc[dt][3]);
;                 *(LAS u32x2*)(lds + ST_OFF + (16 * wave + fr) * 272 + (dt * 16 + fq * 4) * 2) = p;
;             }
; #pragma unroll
;             for (int tt = 0; tt < 4; ++tt) {
;                 f32x4 pw[8];
; #pragma unroll
;                 for (int w = 0; w < 8; ++w) pw[w] = *(const LAS f32x4*)(part + w * 64 + tt * 16 + fq * 4);
;                 __builtin_amdgcn_sched_barrier(0);
;                 const f32x4 ss = ((pw[0] + pw[1]) + (pw[2] + pw[3])) + ((pw[4] + pw[5]) + (pw[6] + pw[7]));
; #pragma unroll
;                 for (int jj = 0; jj < 4; ++jj) {
;                     const float rstd = rsqrtf(ss[jj] * (1.0f / 128.0f) + 1e-6f);
;                     const float z = bf2f(zr[tt][jj]);
;                     const float o = oacc[tt][jj] * rstd * ng * siluf_(z);
;                     obase[(tt * 16 + jj) * PJ1 + ooffl] = (bf16_t)f2bf(o);
.LBB0_414:
	s_or_b64 exec, exec, s[0:1]
	v_add_u32_e32 v139, v135, v150
	ds_read_b128 v[52:55], v139 offset:34816
	v_mul_f32_e32 v48, s18, v168
	v_exp_f32_e32 v138, v48
	v_add_u32_e32 v49, v151, v134
	ds_read_b128 v[56:59], v49
	ds_read_b128 v[48:51], v49 offset:64
	ds_read_b128 v[60:63], v139 offset:34880
	ds_read_b128 v[224:227], v139 offset:50944
	v_pk_mul_f32 v[2:3], v[2:3], v[138:139] op_sel_hi:[1,0]
	v_pk_mul_f32 v[0:1], v[0:1], v[138:139] op_sel_hi:[1,0]
	v_pk_mul_f32 v[6:7], v[6:7], v[138:139] op_sel_hi:[1,0]
	v_pk_mul_f32 v[4:5], v[4:5], v[138:139] op_sel_hi:[1,0]
	s_waitcnt lgkmcnt(3)
	v_mfma_f32_16x16x32_bf16 v[0:3], v[52:55], v[56:59], v[0:3]
	ds_read_b128 v[52:55], v139 offset:37120
	v_pk_mul_f32 v[10:11], v[10:11], v[138:139] op_sel_hi:[1,0]
	v_pk_mul_f32 v[8:9], v[8:9], v[138:139] op_sel_hi:[1,0]
	s_waitcnt lgkmcnt(2)
	v_mfma_f32_16x16x32_bf16 v[0:3], v[60:63], v[48:51], v[0:3]
	ds_read_b128 v[60:63], v139 offset:37184
	v_pk_mul_f32 v[14:15], v[14:15], v[138:139] op_sel_hi:[1,0]
	v_pk_mul_f32 v[12:13], v[12:13], v[138:139] op_sel_hi:[1,0]
	s_waitcnt lgkmcnt(1)
	v_mfma_f32_16x16x32_bf16 v[4:7], v[52:55], v[56:59], v[4:7]
	ds_read_b128 v[52:55], v139 offset:39424
	v_pk_mul_f32 v[18:19], v[18:19], v[138:139] op_sel_hi:[1,0]
	v_pk_mul_f32 v[16:17], v[16:17], v[138:139] op_sel_hi:[1,0]
	s_waitcnt lgkmcnt(1)
	v_mfma_f32_16x16x32_bf16 v[4:7], v[60:63], v[48:51], v[4:7]
	ds_read_b128 v[60:63], v139 offset:39488
	v_pk_mul_f32 v[26:27], v[26:27], v[138:139] op_sel_hi:[1,0]
	ds_read_b128 v[64:67], v139 offset:41792
	s_waitcnt lgkmcnt(2)
	v_mfma_f32_16x16x32_bf16 v[8:11], v[52:55], v[56:59], v[8:11]
	ds_read_b128 v[52:55], v139 offset:41728
	v_pk_mul_f32 v[24:25], v[24:25], v[138:139] op_sel_hi:[1,0]
	s_mov_b64 s[0:1], 0x18003800
	s_waitcnt lgkmcnt(2)
	v_mfma_f32_16x16x32_bf16 v[8:11], v[60:63], v[48:51], v[8:11]
	ds_read_b128 v[60:63], v139 offset:44032
	v_lshl_add_u64 v[134:135], v[118:119], 0, s[0:1]
	s_mov_b64 s[0:1], 0x18005800
	s_waitcnt lgkmcnt(1)
	v_mfma_f32_16x16x32_bf16 v[12:15], v[52:55], v[56:59], v[12:15]
	ds_read_b128 v[52:55], v139 offset:44096
	s_mov_b64 s[2:3], 0x18001800
	v_lshl_add_u64 v[148:149], v[118:119], 0, s[0:1]
	s_waitcnt lgkmcnt(1)
	v_mfma_f32_16x16x32_bf16 v[16:19], v[60:63], v[56:59], v[16:19]
	ds_read_b128 v[60:63], v139 offset:46336
	s_mov_b64 s[0:1], 0x18007800
	v_lshl_add_u64 v[152:153], v[118:119], 0, s[2:3]
	v_mfma_f32_16x16x32_bf16 v[12:15], v[64:67], v[48:51], v[12:15]
	ds_read_b128 v[64:67], v139 offset:46400
	v_lshl_add_u64 v[150:151], v[118:119], 0, s[0:1]
	v_lshl_add_u64 v[118:119], v[124:125], 0, s[2:3]
	s_waitcnt lgkmcnt(2)
	v_mfma_f32_16x16x32_bf16 v[16:19], v[52:55], v[48:51], v[16:19]
	ds_read_b128 v[52:55], v139 offset:48640
	v_pk_mul_f32 v[30:31], v[30:31], v[138:139] op_sel_hi:[1,0]
	v_pk_mul_f32 v[28:29], v[28:29], v[138:139] op_sel_hi:[1,0]
	s_waitcnt lgkmcnt(2)
	v_mfma_f32_16x16x32_bf16 v[24:27], v[60:63], v[56:59], v[24:27]
	ds_read_b128 v[60:63], v139 offset:48704
	v_pk_mul_f32 v[22:23], v[22:23], v[138:139] op_sel_hi:[1,0]
	v_pk_mul_f32 v[20:21], v[20:21], v[138:139] op_sel_hi:[1,0]
	s_waitcnt lgkmcnt(2)
	v_mfma_f32_16x16x32_bf16 v[24:27], v[64:67], v[48:51], v[24:27]
	v_lshl_add_u64 v[66:67], v[122:123], 0, s[2:3]
	ds_read_b128 v[122:125], v139 offset:51008
	s_waitcnt lgkmcnt(0)
	s_waitcnt lgkmcnt(2)
	v_mfma_f32_16x16x32_bf16 v[28:31], v[52:55], v[56:59], v[28:31]
	s_barrier
	v_lshl_add_u64 v[54:55], v[130:131], 0, s[2:3]
	v_mfma_f32_16x16x32_bf16 v[20:23], v[224:227], v[56:59], v[20:23]
	s_nop 0
	s_nop 0
	v_add_u32_e32 v56, v219, v207
	s_waitcnt lgkmcnt(1)
	v_mfma_f32_16x16x32_bf16 v[28:31], v[60:63], v[48:51], v[28:31]
	v_lshl_add_u64 v[60:61], v[128:129], 0, s[2:3]
	v_lshl_add_u64 v[58:59], v[126:127], 0, s[2:3]
	v_lshl_add_u64 v[120:121], v[120:121], 0, s[2:3]
	s_waitcnt lgkmcnt(0)
	v_mfma_f32_16x16x32_bf16 v[20:23], v[122:125], v[48:51], v[20:23]
	s_nop 0
	s_nop 0
	s_nop 0
	s_nop 0
	s_nop 0
	v_cvt_pk_bf16_f32 v48, v0, v1
	s_nop 0
	s_nop 0
	s_nop 0
	s_nop 0
	s_nop 0
	v_cvt_pk_bf16_f32 v49, v2, v3
	v_cvt_pk_bf16_f32 v50, v4, v5
	v_cvt_pk_bf16_f32 v51, v6, v7
	ds_write2_b64 v56, v[48:49], v[50:51] offset1:4
	v_cvt_pk_bf16_f32 v48, v8, v9
	v_cvt_pk_bf16_f32 v49, v10, v11
	v_cvt_pk_bf16_f32 v50, v12, v13
	v_cvt_pk_bf16_f32 v51, v14, v15
	ds_write2_b64 v56, v[48:49], v[50:51] offset0:8 offset1:12
	v_cvt_pk_bf16_f32 v48, v16, v17
	v_cvt_pk_bf16_f32 v49, v18, v19
	v_cvt_pk_bf16_f32 v50, v24, v25
	v_cvt_pk_bf16_f32 v51, v26, v27
	ds_write2_b64 v56, v[48:49], v[50:51] offset0:16 offset1:20
	v_cvt_pk_bf16_f32 v48, v28, v29
	v_cvt_pk_bf16_f32 v49, v30, v31
	v_cvt_pk_bf16_f32 v50, v20, v21
	v_cvt_pk_bf16_f32 v51, v22, v23
	ds_write2_b64 v56, v[48:49], v[50:51] offset0:24 offset1:28
	v_lshl_add_u32 v48, v205, 2, 0
	v_add_u32_e32 v122, 0x25000, v48
	ds_read_b128 v[124:127], v122
	ds_read_b128 v[128:131], v122 offset:256
	ds_read_b128 v[224:227], v122 offset:512
	ds_read_b128 v[228:231], v122 offset:768
	ds_read_b128 v[232:235], v122 offset:1024
	ds_read_b128 v[236:239], v122 offset:1280
	ds_read_b128 v[240:243], v122 offset:1536
	ds_read_b128 v[244:247], v122 offset:1792
	v_lshl_add_u64 v[116:117], v[116:117], 0, s[2:3]
	v_lshl_add_u64 v[52:53], v[132:133], 0, s[2:3]
	v_lshl_add_u64 v[62:63], v[108:109], 0, s[2:3]
	v_lshl_add_u64 v[56:57], v[110:111], 0, s[2:3]
	v_lshl_add_u64 v[50:51], v[112:113], 0, s[2:3]
	v_lshl_add_u64 v[48:49], v[114:115], 0, s[2:3]
	s_waitcnt vmcnt(15)
	v_lshlrev_b32_e32 v112, 16, v223
	v_mul_f32_e32 v111, 0xbfb8aa3b, v112
	v_exp_f32_e32 v113, v111
	s_waitcnt lgkmcnt(7)
	v_mov_b32_e32 v64, v124
	s_waitcnt lgkmcnt(3)
	v_mov_b32_e32 v65, v232
	v_mov_b32_e32 v108, v128
	s_waitcnt lgkmcnt(2)
; #define LAS __attribute__((address_space(3)))
; DI unsigned f2bf(float f) { unsigned u = __float_as_uint(f); u += 0x7FFFu + ((u >> 16) & 1u); return u >> 16; }
; DI float bf2f(unsigned b) { return __uint_as_float(b << 16); }
; DI float siluf_(float x) { return x * __builtin_amdgcn_rcpf(1.0f + __expf(-x)); }
; DI void gdn_unit(const Params& P, bf16_t* proj, const float* gb, int b, int h, LAS unsigned char* lds) {
;     ...
;             for (int tt = 0; tt < 4; ++tt) {
;                 f32x4 pw[8];
; #pragma unroll
;                 for (int w = 0; w < 8; ++w) pw[w] = *(const LAS f32x4*)(part + w * 64 + tt * 16 + fq * 4);
;                 __builtin_amdgcn_sched_barrier(0);
;                 const f32x4 ss = ((pw[0] + pw[1]) + (pw[2] + pw[3])) + ((pw[4] + pw[5]) + (pw[6] + pw[7]));
; #pragma unroll
;                 for (int jj = 0; jj < 4; ++jj) {
;                     const float rstd = rsqrtf(ss[jj] * (1.0f / 128.0f) + 1e-6f);
;                     const float z = bf2f(zr[tt][jj]);
;                     const float o = oacc[tt][jj] * rstd * ng * siluf_(z);
;                     obase[(tt * 16 + jj) * PJ1 + ooffl] = (bf16_t)f2bf(o);
	v_mov_b32_e32 v109, v236
	v_pk_add_f32 v[64:65], v[64:65], v[108:109]
	v_mov_b32_e32 v108, v224
	s_waitcnt lgkmcnt(1)
	v_mov_b32_e32 v109, v240
	v_mov_b32_e32 v110, v228
	s_waitcnt lgkmcnt(0)
	v_mov_b32_e32 v111, v244
	v_pk_add_f32 v[108:109], v[108:109], v[110:111]
	v_mov_b32_e32 v232, v125
	v_pk_add_f32 v[64:65], v[64:65], v[108:109]
	v_add_f32_e32 v108, 1.0, v113
	v_mov_b32_e32 v236, v129
	v_mov_b32_e32 v240, v225
	v_mov_b32_e32 v244, v229
	v_rcp_f32_e32 v113, v108
	v_pk_add_f32 v[108:109], v[232:233], v[236:237]
	v_pk_add_f32 v[110:111], v[240:241], v[244:245]
	s_brev_b32 s2, 60
	v_pk_add_f32 v[108:109], v[108:109], v[110:111]
	v_mov_b32_e32 v111, v64
	v_mov_b32_e32 v110, v108
	v_mov_b32_e32 v64, v109
	v_pk_add_f32 v[108:109], v[110:111], v[64:65]
	v_mov_b64_e32 v[64:65], s[72:73]
	v_pk_fma_f32 v[108:109], v[108:109], s[2:3], v[64:65] op_sel_hi:[1,0,0]
	s_mov_b32 s0, 0x800000
	s_nop 0
	s_waitcnt vmcnt(13)
	v_lshlrev_b32_e32 v114, 16, v221
	s_nop 0
	v_rsq_f32_e32 v109, v109
	v_mul_f32_e32 v110, v113, v112
	s_nop 0
	s_nop 0
	v_mul_f32_e32 v44, v44, v109
	v_mul_f32_e32 v44, v155, v44
	v_mul_f32_e32 v44, v110, v44
	s_nop 0
	v_cvt_pk_bf16_f32 v44, v44, v44
	s_nop 0
	v_lshlrev_b32_e32 v110, 16, v222
	v_mul_f32_e32 v111, 0xbfb8aa3b, v110
	v_exp_f32_e32 v111, v111
	v_rsq_f32_e32 v108, v108
	global_store_short_d16_hi v[152:153], v44, off
	v_add_f32_e32 v109, 1.0, v111
	v_rcp_f32_e32 v109, v109
	s_nop 0
	v_mov_b32_e32 v44, v108
	v_mul_f32_e32 v44, v45, v44
	v_mul_f32_e32 v111, 0xbfb8aa3b, v114
	v_mul_f32_e32 v44, v155, v44
	v_mul_f32_e32 v45, v109, v110
	v_exp_f32_e32 v115, v111
	v_mul_f32_e32 v112, v45, v44
	v_mov_b32_e32 v44, v126
	v_mov_b32_e32 v45, v234
	v_mov_b32_e32 v108, v130
	v_mov_b32_e32 v109, v238
	v_pk_add_f32 v[44:45], v[44:45], v[108:109]
	v_mov_b32_e32 v108, v226
	v_mov_b32_e32 v109, v242
	v_mov_b32_e32 v110, v230
	v_mov_b32_e32 v111, v246
	v_pk_add_f32 v[108:109], v[108:109], v[110:111]
	v_mov_b32_e32 v234, v127
	v_pk_add_f32 v[44:45], v[44:45], v[108:109]
	v_add_f32_e32 v108, 1.0, v115
	v_mov_b32_e32 v238, v131
	v_mov_b32_e32 v242, v227
	v_mov_b32_e32 v246, v231
	v_rcp_f32_e32 v115, v108
	v_pk_add_f32 v[108:109], v[234:235], v[238:239]
	v_pk_add_f32 v[110:111], v[242:243], v[246:247]
	s_nop 0
	v_pk_add_f32 v[108:109], v[108:109], v[110:111]
	v_mov_b32_e32 v111, v44
	v_mov_b32_e32 v110, v108
	v_mov_b32_e32 v44, v109
	v_pk_add_f32 v[44:45], v[110:111], v[44:45]
	s_nop 0
	v_pk_fma_f32 v[44:45], v[44:45], s[2:3], v[64:65] op_sel_hi:[1,0,0]
	s_nop 0
	s_nop 0
	s_nop 0
	s_nop 1
	s_nop 0
	v_rsq_f32_e32 v45, v45
	v_cvt_pk_bf16_f32 v108, v112, v112
	global_store_short_d16_hi v[134:135], v108, off
	v_mul_f32_e32 v108, v115, v114
	s_nop 0
	s_nop 0
	v_mul_f32_e32 v45, v46, v45
	v_mul_f32_e32 v45, v155, v45
	v_mul_f32_e32 v45, v108, v45
	s_nop 0
	v_cvt_pk_bf16_f32 v45, v45, v45
	s_nop 0
	s_waitcnt vmcnt(14)
	v_lshlrev_b32_e32 v108, 16, v220
	v_mul_f32_e32 v109, 0xbfb8aa3b, v108
	v_exp_f32_e32 v109, v109
	v_rsq_f32_e32 v44, v44
	global_store_short_d16_hi v[148:149], v45, off
	v_add_f32_e32 v46, 1.0, v109
	v_rcp_f32_e32 v46, v46
	s_nop 0
	s_nop 0
	v_mul_f32_e32 v44, v47, v44
	v_mul_f32_e32 v123, v155, v44
	v_mul_f32_e32 v138, v46, v108
	ds_read_b128 v[44:47], v122 offset:64
	ds_read_b128 v[108:111], v122 offset:320
	ds_read_b128 v[112:115], v122 offset:576
	ds_read_b128 v[124:127], v122 offset:832
	ds_read_b128 v[128:131], v122 offset:1088
	ds_read_b128 v[132:135], v122 offset:1344
	ds_read_b128 v[220:223], v122 offset:1600
	ds_read_b128 v[224:227], v122 offset:1856
	v_mul_f32_e32 v123, v138, v123
	s_nop 0
	v_cvt_pk_bf16_f32 v123, v123, v123
	global_store_short_d16_hi v[150:151], v123, off
	s_waitcnt lgkmcnt(7)
	v_mov_b32_e32 v138, v44
	s_waitcnt lgkmcnt(3)
	v_mov_b32_e32 v139, v128
	v_mov_b32_e32 v140, v108
	s_waitcnt lgkmcnt(2)
	v_mov_b32_e32 v141, v132
	v_pk_add_f32 v[138:139], v[138:139], v[140:141]
	v_mov_b32_e32 v140, v112
	s_waitcnt vmcnt(15)
	v_lshlrev_b32_e32 v112, 16, v218
	v_mul_f32_e32 v44, 0xbfb8aa3b, v112
	v_exp_f32_e32 v44, v44
	s_waitcnt lgkmcnt(1)
	v_mov_b32_e32 v141, v220
	v_mov_b32_e32 v144, v124
	s_waitcnt lgkmcnt(0)
	v_mov_b32_e32 v145, v224
	v_add_f32_e32 v44, 1.0, v44
	v_mov_b32_e32 v128, v45
	v_mov_b32_e32 v132, v109
	v_mov_b32_e32 v220, v113
	v_mov_b32_e32 v224, v125
	v_pk_add_f32 v[140:141], v[140:141], v[144:145]
	v_rcp_f32_e32 v123, v44
	v_pk_add_f32 v[44:45], v[128:129], v[132:133]
	v_pk_add_f32 v[108:109], v[220:221], v[224:225]
	v_pk_add_f32 v[138:139], v[138:139], v[140:141]
	v_pk_add_f32 v[44:45], v[44:45], v[108:109]
	v_mov_b32_e32 v109, v138
	v_mov_b32_e32 v108, v44
	v_mov_b32_e32 v138, v45
	v_pk_add_f32 v[44:45], v[108:109], v[138:139]
	s_nop 0
	v_pk_fma_f32 v[44:45], v[44:45], s[2:3], v[64:65] op_sel_hi:[1,0,0]
	s_nop 0
	s_nop 0
	s_nop 0
	s_nop 1
	s_nop 0
	v_rsq_f32_e32 v45, v45
	v_mul_f32_e32 v108, v123, v112
	s_nop 0
	s_nop 0
	v_mul_f32_e32 v40, v40, v45
	v_mul_f32_e32 v40, v155, v40
	v_mul_f32_e32 v40, v108, v40
	s_nop 0
	v_cvt_pk_bf16_f32 v40, v40, v40
	s_nop 0
	s_waitcnt vmcnt(14)
	v_lshlrev_b32_e32 v108, 16, v217
	v_mul_f32_e32 v109, 0xbfb8aa3b, v108
	v_exp_f32_e32 v109, v109
	v_rsq_f32_e32 v44, v44
	global_store_short_d16_hi v[120:121], v40, off
	v_add_f32_e32 v45, 1.0, v109
	v_rcp_f32_e32 v45, v45
	s_nop 0
	v_mov_b32_e32 v40, v44
	v_mul_f32_e32 v40, v41, v40
	v_mul_f32_e32 v40, v155, v40
	v_mul_f32_e32 v41, v45, v108
	v_mov_b32_e32 v44, v110
	s_waitcnt vmcnt(14)
; #define LAS __attribute__((address_space(3)))
; DI unsigned f2bf(float f) { unsigned u = __float_as_uint(f); u += 0x7FFFu + ((u >> 16) & 1u); return u >> 16; }
; DI float bf2f(unsigned b) { return __uint_as_float(b << 16); }
; DI float siluf_(float x) { return x * __builtin_amdgcn_rcpf(1.0f + __expf(-x)); }
; DI void gdn_unit(const Params& P, bf16_t* proj, const float* gb, int b, int h, LAS unsigned char* lds) {
;     ...
;             for (int tt = 0; tt < 4; ++tt) {
;                 f32x4 pw[8];
; #pragma unroll
;                 for (int w = 0; w < 8; ++w) pw[w] = *(const LAS f32x4*)(part + w * 64 + tt * 16 + fq * 4);
;                 __builtin_amdgcn_sched_barrier(0);
;                 const f32x4 ss = ((pw[0] + pw[1]) + (pw[2] + pw[3])) + ((pw[4] + pw[5]) + (pw[6] + pw[7]));
; #pragma unroll
;                 for (int jj = 0; jj < 4; ++jj) {
;                     const float rstd = rsqrtf(ss[jj] * (1.0f / 128.0f) + 1e-6f);
;                     const float z = bf2f(zr[tt][jj]);
;                     const float o = oacc[tt][jj] * rstd * ng * siluf_(z);
;                     obase[(tt * 16 + jj) * PJ1 + ooffl] = (bf16_t)f2bf(o);
	v_lshlrev_b32_e32 v110, 16, v216
	v_mul_f32_e32 v112, v41, v40
	v_mov_b32_e32 v40, v46
	v_mul_f32_e32 v46, 0xbfb8aa3b, v110
	v_exp_f32_e32 v46, v46
	v_mov_b32_e32 v41, v130
	v_mov_b32_e32 v45, v134
	v_pk_add_f32 v[40:41], v[40:41], v[44:45]
	v_mov_b32_e32 v44, v114
	v_mov_b32_e32 v45, v222
	v_mov_b32_e32 v108, v126
	v_mov_b32_e32 v109, v226
	v_pk_add_f32 v[44:45], v[44:45], v[108:109]
	v_mov_b32_e32 v130, v47
	v_pk_add_f32 v[40:41], v[40:41], v[44:45]
	v_add_f32_e32 v44, 1.0, v46
	v_mov_b32_e32 v134, v111
	v_mov_b32_e32 v222, v115
	v_mov_b32_e32 v226, v127
	v_rcp_f32_e32 v108, v44
	v_pk_add_f32 v[44:45], v[130:131], v[134:135]
	v_pk_add_f32 v[46:47], v[222:223], v[226:227]
	s_nop 0
	v_pk_add_f32 v[44:45], v[44:45], v[46:47]
	v_mov_b32_e32 v47, v40
	v_mov_b32_e32 v46, v44
	v_mov_b32_e32 v40, v45
	v_pk_add_f32 v[40:41], v[46:47], v[40:41]
	s_nop 0
	v_pk_fma_f32 v[40:41], v[40:41], s[2:3], v[64:65] op_sel_hi:[1,0,0]
	s_nop 0
	s_nop 0
	s_nop 0
	s_nop 1
	s_nop 0
	v_rsq_f32_e32 v41, v41
	v_cvt_pk_bf16_f32 v44, v112, v112
	global_store_short_d16_hi v[118:119], v44, off
	v_mul_f32_e32 v44, v108, v110
	s_nop 0
	s_nop 0
	v_mul_f32_e32 v41, v42, v41
	v_mul_f32_e32 v41, v155, v41
	v_mul_f32_e32 v41, v44, v41
	s_nop 0
	v_cvt_pk_bf16_f32 v41, v41, v41
	s_nop 0
	s_waitcnt vmcnt(14)
	v_lshlrev_b32_e32 v44, 16, v215
	v_mul_f32_e32 v45, 0xbfb8aa3b, v44
	v_exp_f32_e32 v45, v45
	v_rsq_f32_e32 v40, v40
	global_store_short_d16_hi v[116:117], v41, off
	v_add_f32_e32 v42, 1.0, v45
	v_rcp_f32_e32 v42, v42
	s_nop 0
	s_nop 0
	v_mul_f32_e32 v40, v43, v40
	v_mul_f32_e32 v120, v155, v40
	v_mul_f32_e32 v121, v42, v44
	ds_read_b128 v[40:43], v122 offset:128
	ds_read_b128 v[44:47], v122 offset:384
	ds_read_b128 v[108:111], v122 offset:640
	ds_read_b128 v[112:115], v122 offset:896
	ds_read_b128 v[116:119], v122 offset:1152
	ds_read_b128 v[124:127], v122 offset:1408
	ds_read_b128 v[128:131], v122 offset:1664
	ds_read_b128 v[132:135], v122 offset:1920
	v_mul_f32_e32 v120, v121, v120
	s_nop 0
	v_cvt_pk_bf16_f32 v120, v120, v120
	global_store_short_d16_hi v[66:67], v120, off
	s_waitcnt lgkmcnt(7)
	v_mov_b32_e32 v66, v40
	s_waitcnt lgkmcnt(3)
	v_mov_b32_e32 v67, v116
	v_mov_b32_e32 v120, v44
	s_waitcnt lgkmcnt(2)
	v_mov_b32_e32 v121, v124
	v_pk_add_f32 v[66:67], v[66:67], v[120:121]
	v_mov_b32_e32 v120, v108
	s_waitcnt vmcnt(15)
	v_lshlrev_b32_e32 v108, 16, v214
	v_mul_f32_e32 v40, 0xbfb8aa3b, v108
	v_exp_f32_e32 v40, v40
	s_waitcnt lgkmcnt(1)
	v_mov_b32_e32 v121, v128
	v_mov_b32_e32 v138, v112
	s_waitcnt lgkmcnt(0)
	v_mov_b32_e32 v139, v132
	v_add_f32_e32 v40, 1.0, v40
	v_mov_b32_e32 v116, v41
	v_mov_b32_e32 v124, v45
	v_mov_b32_e32 v128, v109
	v_mov_b32_e32 v132, v113
	v_pk_add_f32 v[120:121], v[120:121], v[138:139]
	v_rcp_f32_e32 v112, v40
	v_pk_add_f32 v[40:41], v[116:117], v[124:125]
	v_pk_add_f32 v[44:45], v[128:129], v[132:133]
	v_pk_add_f32 v[66:67], v[66:67], v[120:121]
	v_pk_add_f32 v[40:41], v[40:41], v[44:45]
	v_mov_b32_e32 v45, v66
	v_mov_b32_e32 v44, v40
	v_mov_b32_e32 v66, v41
	v_pk_add_f32 v[40:41], v[44:45], v[66:67]
	s_nop 0
	v_pk_fma_f32 v[40:41], v[40:41], s[2:3], v[64:65] op_sel_hi:[1,0,0]
	s_nop 0
	s_nop 0
	s_nop 0
	s_nop 1
	s_nop 0
	v_rsq_f32_e32 v41, v41
	v_mul_f32_e32 v44, v112, v108
	s_nop 0
	s_nop 0
	v_mul_f32_e32 v36, v36, v41
	v_mul_f32_e32 v36, v155, v36
	v_mul_f32_e32 v36, v44, v36
	s_nop 0
	v_cvt_pk_bf16_f32 v36, v36, v36
	s_nop 0
	s_waitcnt vmcnt(14)
	v_lshlrev_b32_e32 v44, 16, v213
	v_mul_f32_e32 v45, 0xbfb8aa3b, v44
	v_exp_f32_e32 v45, v45
	v_rsq_f32_e32 v40, v40
	global_store_short_d16_hi v[60:61], v36, off
	v_add_f32_e32 v41, 1.0, v45
	v_rcp_f32_e32 v41, v41
	s_nop 0
	v_mov_b32_e32 v36, v40
	v_mul_f32_e32 v36, v37, v36
	v_mul_f32_e32 v36, v155, v36
	v_mul_f32_e32 v37, v41, v44
	v_mov_b32_e32 v40, v46
	s_waitcnt vmcnt(14)
	v_lshlrev_b32_e32 v46, 16, v212
	v_mul_f32_e32 v60, v37, v36
	v_mov_b32_e32 v36, v42
	v_mul_f32_e32 v42, 0xbfb8aa3b, v46
	v_exp_f32_e32 v42, v42
	v_mov_b32_e32 v37, v118
	v_mov_b32_e32 v41, v126
	v_pk_add_f32 v[36:37], v[36:37], v[40:41]
	v_mov_b32_e32 v40, v110
	v_mov_b32_e32 v41, v130
	v_mov_b32_e32 v44, v114
	v_mov_b32_e32 v45, v134
	v_pk_add_f32 v[40:41], v[40:41], v[44:45]
	v_mov_b32_e32 v118, v43
	v_pk_add_f32 v[36:37], v[36:37], v[40:41]
	v_add_f32_e32 v40, 1.0, v42
	v_mov_b32_e32 v126, v47
	v_mov_b32_e32 v130, v111
	v_mov_b32_e32 v134, v115
	v_rcp_f32_e32 v44, v40
	v_pk_add_f32 v[40:41], v[118:119], v[126:127]
	v_pk_add_f32 v[42:43], v[130:131], v[134:135]
	s_nop 0
	v_pk_add_f32 v[40:41], v[40:41], v[42:43]
	v_mov_b32_e32 v43, v36
	v_mov_b32_e32 v42, v40
	v_mov_b32_e32 v36, v41
	v_pk_add_f32 v[36:37], v[42:43], v[36:37]
	s_nop 0
	v_pk_fma_f32 v[36:37], v[36:37], s[2:3], v[64:65] op_sel_hi:[1,0,0]
	s_nop 0
	s_nop 0
	s_nop 0
	s_nop 1
	s_nop 0
	v_rsq_f32_e32 v37, v37
	v_cvt_pk_bf16_f32 v40, v60, v60
	global_store_short_d16_hi v[58:59], v40, off
	v_mul_f32_e32 v40, v44, v46
	s_nop 0
	s_nop 0
	v_mul_f32_e32 v37, v38, v37
	v_mul_f32_e32 v37, v155, v37
	v_mul_f32_e32 v37, v40, v37
	s_nop 0
	v_cvt_pk_bf16_f32 v37, v37, v37
	s_nop 0
	s_waitcnt vmcnt(14)
; #define LAS __attribute__((address_space(3)))
; DI unsigned f2bf(float f) { unsigned u = __float_as_uint(f); u += 0x7FFFu + ((u >> 16) & 1u); return u >> 16; }
; DI float bf2f(unsigned b) { return __uint_as_float(b << 16); }
; DI float siluf_(float x) { return x * __builtin_amdgcn_rcpf(1.0f + __expf(-x)); }
; DI void gdn_unit(const Params& P, bf16_t* proj, const float* gb, int b, int h, LAS unsigned char* lds) {
;     ...
;             for (int tt = 0; tt < 4; ++tt) {
;                 f32x4 pw[8];
; #pragma unroll
;                 for (int w = 0; w < 8; ++w) pw[w] = *(const LAS f32x4*)(part + w * 64 + tt * 16 + fq * 4);
;                 __builtin_amdgcn_sched_barrier(0);
;                 const f32x4 ss = ((pw[0] + pw[1]) + (pw[2] + pw[3])) + ((pw[4] + pw[5]) + (pw[6] + pw[7]));
; #pragma unroll
;                 for (int jj = 0; jj < 4; ++jj) {
;                     const float rstd = rsqrtf(ss[jj] * (1.0f / 128.0f) + 1e-6f);
;                     const float z = bf2f(zr[tt][jj]);
;                     const float o = oacc[tt][jj] * rstd * ng * siluf_(z);
;                     obase[(tt * 16 + jj) * PJ1 + ooffl] = (bf16_t)f2bf(o);
;                 }
;             }
;         }
;     }
	v_lshlrev_b32_e32 v40, 16, v211
	v_mul_f32_e32 v41, 0xbfb8aa3b, v40
	v_exp_f32_e32 v41, v41
	v_rsq_f32_e32 v36, v36
	global_store_short_d16_hi v[54:55], v37, off
	v_add_f32_e32 v38, 1.0, v41
	v_rcp_f32_e32 v38, v38
	s_nop 0
	s_nop 0
	v_mul_f32_e32 v36, v39, v36
	v_mul_f32_e32 v54, v155, v36
	v_mul_f32_e32 v55, v38, v40
	ds_read_b128 v[36:39], v122 offset:192
	ds_read_b128 v[40:43], v122 offset:448
	ds_read_b128 v[44:47], v122 offset:704
	ds_read_b128 v[58:61], v122 offset:960
	ds_read_b128 v[108:111], v122 offset:1216
	ds_read_b128 v[112:115], v122 offset:1472
	ds_read_b128 v[116:119], v122 offset:1728
	ds_read_b128 v[120:123], v122 offset:1984
	v_mul_f32_e32 v54, v55, v54
	s_nop 0
	v_cvt_pk_bf16_f32 v54, v54, v54
	global_store_short_d16_hi v[52:53], v54, off
	s_waitcnt lgkmcnt(7)
	v_mov_b32_e32 v52, v36
	s_waitcnt lgkmcnt(3)
	v_mov_b32_e32 v53, v108
	v_mov_b32_e32 v54, v40
	s_waitcnt lgkmcnt(2)
	v_mov_b32_e32 v55, v112
	v_pk_add_f32 v[52:53], v[52:53], v[54:55]
	v_mov_b32_e32 v54, v44
	s_waitcnt vmcnt(15)
	v_lshlrev_b32_e32 v44, 16, v210
	v_mul_f32_e32 v36, 0xbfb8aa3b, v44
	v_exp_f32_e32 v36, v36
	s_waitcnt lgkmcnt(1)
	v_mov_b32_e32 v55, v116
	v_mov_b32_e32 v66, v58
	s_waitcnt lgkmcnt(0)
	v_mov_b32_e32 v67, v120
	v_pk_add_f32 v[54:55], v[54:55], v[66:67]
	v_add_f32_e32 v36, 1.0, v36
	v_mov_b32_e32 v108, v37
	v_mov_b32_e32 v112, v41
	v_mov_b32_e32 v116, v45
	v_mov_b32_e32 v120, v59
	v_pk_add_f32 v[52:53], v[52:53], v[54:55]
	v_rcp_f32_e32 v54, v36
	v_pk_add_f32 v[36:37], v[108:109], v[112:113]
	v_pk_add_f32 v[40:41], v[116:117], v[120:121]
	s_add_u32 s14, s14, 0x80000
	v_pk_add_f32 v[36:37], v[36:37], v[40:41]
	v_mov_b32_e32 v41, v52
	v_mov_b32_e32 v40, v36
	v_mov_b32_e32 v52, v37
	v_pk_add_f32 v[36:37], v[40:41], v[52:53]
	s_addc_u32 s15, s15, 0
	v_pk_fma_f32 v[36:37], v[36:37], s[2:3], v[64:65] op_sel_hi:[1,0,0]
	s_add_i32 s42, s42, 64
	s_nop 0
	s_mov_b32 s18, 0x800000
	s_cmp_lg_u32 s14, 0x1000000
	s_nop 0
	v_rsq_f32_e32 v37, v37
	v_mul_f32_e32 v40, v54, v44
	s_nop 0
	s_nop 0
	v_mul_f32_e32 v32, v32, v37
	v_mul_f32_e32 v32, v155, v32
	v_mul_f32_e32 v32, v40, v32
	s_nop 0
	v_cvt_pk_bf16_f32 v32, v32, v32
	s_nop 0
	s_waitcnt vmcnt(14)
	v_lshlrev_b32_e32 v40, 16, v209
	v_mul_f32_e32 v41, 0xbfb8aa3b, v40
	v_exp_f32_e32 v41, v41
	v_rsq_f32_e32 v36, v36
	global_store_short_d16_hi v[62:63], v32, off
	v_add_f32_e32 v37, 1.0, v41
	v_rcp_f32_e32 v37, v37
	s_nop 0
	v_mov_b32_e32 v32, v36
	v_mul_f32_e32 v32, v33, v32
	v_mul_f32_e32 v32, v155, v32
	v_mul_f32_e32 v33, v37, v40
	v_mov_b32_e32 v36, v42
	s_waitcnt vmcnt(14)
	v_lshlrev_b32_e32 v42, 16, v208
	v_mul_f32_e32 v44, v33, v32
	v_mov_b32_e32 v32, v38
	v_mul_f32_e32 v38, 0xbfb8aa3b, v42
	v_exp_f32_e32 v38, v38
	v_mov_b32_e32 v33, v110
	v_mov_b32_e32 v37, v114
	v_pk_add_f32 v[32:33], v[32:33], v[36:37]
	v_mov_b32_e32 v36, v46
	v_mov_b32_e32 v37, v118
	v_mov_b32_e32 v40, v60
	v_mov_b32_e32 v41, v122
	v_pk_add_f32 v[36:37], v[36:37], v[40:41]
	v_mov_b32_e32 v110, v39
	v_pk_add_f32 v[32:33], v[32:33], v[36:37]
	v_add_f32_e32 v36, 1.0, v38
	v_mov_b32_e32 v114, v43
	v_mov_b32_e32 v118, v47
	v_mov_b32_e32 v122, v61
	v_rcp_f32_e32 v40, v36
	v_pk_add_f32 v[36:37], v[110:111], v[114:115]
	v_pk_add_f32 v[38:39], v[118:119], v[122:123]
	v_bfe_u32 v45, v44, 16, 1
	v_pk_add_f32 v[36:37], v[36:37], v[38:39]
	v_mov_b32_e32 v39, v32
	v_mov_b32_e32 v38, v36
	v_mov_b32_e32 v32, v37
	v_pk_add_f32 v[32:33], v[38:39], v[32:33]
	s_nop 0
	v_pk_fma_f32 v[32:33], v[32:33], s[2:3], v[64:65] op_sel_hi:[1,0,0]
	s_nop 0
	s_nop 0
	s_nop 0
	s_nop 1
	s_nop 0
	v_rsq_f32_e32 v33, v33
	v_add3_u32 v36, v44, v45, s68
	global_store_short_d16_hi v[56:57], v36, off
	v_mul_f32_e32 v36, v40, v42
	s_nop 0
	s_nop 0
	v_mul_f32_e32 v33, v34, v33
	v_mul_f32_e32 v33, v155, v33
	v_mul_f32_e32 v33, v36, v33
	s_nop 0
	v_cvt_pk_bf16_f32 v33, v33, v33
	s_nop 0
	s_waitcnt vmcnt(14)
	v_lshlrev_b32_e32 v36, 16, v206
	v_mul_f32_e32 v37, 0xbfb8aa3b, v36
	v_exp_f32_e32 v37, v37
	v_rsq_f32_e32 v32, v32
	global_store_short_d16_hi v[50:51], v33, off
	v_add_f32_e32 v34, 1.0, v37
	v_rcp_f32_e32 v34, v34
	s_nop 0
	s_nop 0
	v_mul_f32_e32 v32, v35, v32
	v_mul_f32_e32 v32, v155, v32
	v_mul_f32_e32 v33, v34, v36
	v_mul_f32_e32 v32, v33, v32
	v_bfe_u32 v33, v32, 16, 1
	v_add3_u32 v32, v32, v33, s68
	global_store_short_d16_hi v[48:49], v32, off
	s_cbranch_scc0 .LBB0_336

; DI float bflo(unsigned w) { return __uint_as_float(w << 16); }
; DI float bfhi(unsigned w) { return __uint_as_float(w & 0xffff0000u); }
; DI float siluf_(float x) { return x * __builtin_amdgcn_rcpf(1.0f + __expf(-x)); }
; DI float wave_sum(float v) { v = row16_sum(v); return (rdlane(v, 0) + rdlane(v, 16)) + (rdlane(v, 32) + rdlane(v, 48)); }
; DI void gdn_unit(const Params& P, bf16_t* proj, const float* gb, int b, int h, LAS unsigned char* lds) {
;     ...
;         for (int w = 0; w < 3; ++w) {
;             const f32x2 (&cw)[4] = cwr[w];
;             const unsigned (&raw)[11] = rawq[w];
;             float o0[8], o1[8];
; #pragma unroll
;             for (int i = 0; i < 8; ++i) {
;                 float a0 = 0.f, a1 = 0.f;
; #pragma unroll
;                 for (int j = 0; j < 4; ++j) { a0 += cw[j][0] * bflo(raw[i + j]); a1 += cw[j][1] * bfhi(raw[i + j]); }
;                 a0 = siluf_(a0); a1 = siluf_(a1);
;                 if (w < 2) {
;                     const float ss = wave_sum(a0 * a0 + a1 * a1);
;                     const float rs = rsqrtf(ss + 1e-6f) * (w == 0 ? 0.08838834764831845f : 1.0f);
;                     a0 *= rs; a1 *= rs;
;                 }
;                 o0[i] = a0; o1[i] = a1;
.LBB0_423:
	v_and_b32_e32 v63, 0xffff0000, v136
	v_lshlrev_b32_e32 v62, 16, v136
	v_and_b32_e32 v57, 0xffff0000, v157
	v_lshlrev_b32_e32 v56, 16, v157
	v_pk_fma_f32 v[62:63], v[68:69], v[62:63], 0 op_sel_hi:[1,1,0]
	v_and_b32_e32 v59, 0xffff0000, v156
	v_lshlrev_b32_e32 v58, 16, v156
	v_pk_fma_f32 v[110:111], v[68:69], v[56:57], 0 op_sel_hi:[1,1,0]
	v_pk_fma_f32 v[56:57], v[70:71], v[56:57], v[62:63]
	v_and_b32_e32 v61, 0xffff0000, v160
	v_lshlrev_b32_e32 v60, 16, v160
	v_pk_fma_f32 v[56:57], v[72:73], v[58:59], v[56:57]
	v_pk_fma_f32 v[64:65], v[68:69], v[58:59], 0 op_sel_hi:[1,1,0]
	v_pk_fma_f32 v[56:57], v[74:75], v[60:61], v[56:57]
	v_pk_fma_f32 v[110:111], v[70:71], v[58:59], v[110:111]
	v_mul_f32_e32 v58, 0xbfb8aa3b, v57
	v_exp_f32_e32 v58, v58
	s_movk_i32 s0, 0x11c
	v_mul_lo_u32 v55, v67, s0
	s_mov_b32 s26, 0x800000
	v_add_f32_e32 v58, 1.0, v58
	v_rcp_f32_e32 v59, v58
	v_mul_f32_e32 v58, 0xbfb8aa3b, v56
	v_exp_f32_e32 v58, v58
	v_and_b32_e32 v53, 0xffff0000, v159
	v_lshlrev_b32_e32 v52, 16, v159
	v_pk_fma_f32 v[50:51], v[68:69], v[60:61], 0 op_sel_hi:[1,1,0]
	v_add_f32_e32 v58, 1.0, v58
	v_rcp_f32_e32 v58, v58
	v_pk_fma_f32 v[64:65], v[70:71], v[60:61], v[64:65]
	v_and_b32_e32 v49, 0xffff0000, v158
	v_lshlrev_b32_e32 v48, 16, v158
	v_pk_mul_f32 v[58:59], v[56:57], v[58:59]
	v_pk_fma_f32 v[46:47], v[68:69], v[52:53], 0 op_sel_hi:[1,1,0]
	v_pk_mul_f32 v[56:57], v[58:59], v[58:59]
	v_pk_fma_f32 v[50:51], v[70:71], v[52:53], v[50:51]
	v_add_f32_e32 v56, v57, v56
	v_and_b32_e32 v45, 0xffff0000, v176
	v_lshlrev_b32_e32 v44, 16, v176
	v_add_f32_dpp v56, v56, v56 quad_perm:[1,0,3,2] row_mask:0xf bank_mask:0xf bound_ctrl:1
	v_pk_fma_f32 v[42:43], v[68:69], v[48:49], 0 op_sel_hi:[1,1,0]
	v_pk_fma_f32 v[46:47], v[70:71], v[48:49], v[46:47]
	v_add_f32_dpp v56, v56, v56 quad_perm:[2,3,0,1] row_mask:0xf bank_mask:0xf bound_ctrl:1
	v_and_b32_e32 v33, 0xffff0000, v161
	v_lshlrev_b32_e32 v32, 16, v161
	v_add_f32_dpp v56, v56, v56 row_half_mirror row_mask:0xf bank_mask:0xf bound_ctrl:1
	v_pk_fma_f32 v[40:41], v[68:69], v[44:45], 0 op_sel_hi:[1,1,0]
	v_pk_fma_f32 v[42:43], v[70:71], v[44:45], v[42:43]
	v_add_f32_dpp v56, v56, v56 row_mirror row_mask:0xf bank_mask:0xf bound_ctrl:1
	v_and_b32_e32 v35, 0xffff0000, v179
	v_readlane_b32 s2, v56, 16
	v_readlane_b32 s3, v56, 48
	v_readlane_b32 s0, v56, 0
	v_readlane_b32 s1, v56, 32
	v_mov_b32_e32 v56, s2
	v_mov_b32_e32 v57, s3
	v_pk_add_f32 v[56:57], s[0:1], v[56:57]
	v_lshlrev_b32_e32 v34, 16, v179
	v_add_f32_e32 v56, v56, v57
	v_add_f32_e32 v56, 0x358637bd, v56
	s_nop 0
	s_nop 0
	v_pk_fma_f32 v[42:43], v[72:73], v[32:33], v[42:43]
	s_nop 0
	v_rsq_f32_e32 v56, v56
	v_pk_fma_f32 v[42:43], v[74:75], v[34:35], v[42:43]
	v_pk_fma_f32 v[40:41], v[70:71], v[32:33], v[40:41]
	v_and_b32_e32 v37, 0xffff0000, v178
	s_nop 0
	v_mul_f32_e32 v56, 0x3db504f3, v56
	v_mul_f32_e32 v57, v58, v56
	v_mul_f32_e32 v56, v59, v56
	v_pk_fma_f32 v[58:59], v[72:73], v[60:61], v[110:111]
	v_lshlrev_b32_e32 v36, 16, v178
	v_pk_fma_f32 v[58:59], v[74:75], v[52:53], v[58:59]
	v_pk_fma_f32 v[52:53], v[72:73], v[52:53], v[64:65]
	v_mul_f32_e32 v60, 0xbfb8aa3b, v59
	v_exp_f32_e32 v60, v60
	v_pk_fma_f32 v[52:53], v[74:75], v[48:49], v[52:53]
	v_pk_fma_f32 v[48:49], v[72:73], v[48:49], v[50:51]
	v_pk_fma_f32 v[40:41], v[72:73], v[34:35], v[40:41]
	v_add_f32_e32 v60, 1.0, v60
	v_rcp_f32_e32 v61, v60
	v_mul_f32_e32 v60, 0xbfb8aa3b, v58
	v_exp_f32_e32 v60, v60
	v_pk_fma_f32 v[48:49], v[74:75], v[44:45], v[48:49]
	v_pk_fma_f32 v[44:45], v[72:73], v[44:45], v[46:47]
	v_mul_f32_e32 v50, 0xbfb8aa3b, v49
	v_add_f32_e32 v60, 1.0, v60
	v_rcp_f32_e32 v60, v60
	v_exp_f32_e32 v50, v50
	v_pk_fma_f32 v[44:45], v[74:75], v[32:33], v[44:45]
	v_pk_fma_f32 v[40:41], v[74:75], v[36:37], v[40:41]
	v_pk_mul_f32 v[60:61], v[58:59], v[60:61]
	v_add_f32_e32 v50, 1.0, v50
	v_pk_mul_f32 v[58:59], v[60:61], v[60:61]
	v_rcp_f32_e32 v51, v50
	v_add_f32_e32 v58, v59, v58
	v_mul_f32_e32 v50, 0xbfb8aa3b, v48
	v_exp_f32_e32 v50, v50
	v_add_f32_dpp v58, v58, v58 quad_perm:[1,0,3,2] row_mask:0xf bank_mask:0xf bound_ctrl:1
	v_mul_f32_e32 v46, 0xbfb8aa3b, v45
	v_exp_f32_e32 v46, v46
	v_add_f32_dpp v58, v58, v58 quad_perm:[2,3,0,1] row_mask:0xf bank_mask:0xf bound_ctrl:1
	v_add_f32_e32 v50, 1.0, v50
	v_rcp_f32_e32 v50, v50
	v_add_f32_dpp v58, v58, v58 row_half_mirror row_mask:0xf bank_mask:0xf bound_ctrl:1
	v_add_f32_e32 v46, 1.0, v46
	v_rcp_f32_e32 v47, v46
	v_add_f32_dpp v58, v58, v58 row_mirror row_mask:0xf bank_mask:0xf bound_ctrl:1
	v_mul_f32_e32 v46, 0xbfb8aa3b, v44
	v_readlane_b32 s2, v58, 16
	v_readlane_b32 s3, v58, 48
	v_readlane_b32 s0, v58, 0
	v_readlane_b32 s1, v58, 32
	v_mov_b32_e32 v58, s2
	v_mov_b32_e32 v59, s3
	v_pk_add_f32 v[58:59], s[0:1], v[58:59]
	v_exp_f32_e32 v46, v46
	v_add_f32_e32 v58, v58, v59
	v_add_f32_e32 v58, 0x358637bd, v58
	s_nop 0
	s_nop 0
	v_pk_mul_f32 v[48:49], v[48:49], v[50:51]
	s_nop 0
	v_rsq_f32_e32 v58, v58
	v_pk_mul_f32 v[50:51], v[48:49], v[48:49]
	v_add_f32_e32 v46, 1.0, v46
	v_add_f32_e32 v50, v51, v50
	s_nop 0
	s_nop 0
	v_mul_f32_e32 v58, 0x3db504f3, v58
	v_mul_f32_e32 v59, v60, v58
	v_mul_f32_e32 v60, 0xbfb8aa3b, v53
	v_exp_f32_e32 v60, v60
	v_mul_f32_e32 v58, v61, v58
	v_add_f32_dpp v50, v50, v50 quad_perm:[1,0,3,2] row_mask:0xf bank_mask:0xf bound_ctrl:1
	v_rcp_f32_e32 v46, v46
	v_add_f32_e32 v60, 1.0, v60
	v_rcp_f32_e32 v61, v60
	v_mul_f32_e32 v60, 0xbfb8aa3b, v52
	v_exp_f32_e32 v60, v60
	v_add_f32_dpp v50, v50, v50 quad_perm:[2,3,0,1] row_mask:0xf bank_mask:0xf bound_ctrl:1
	v_pk_mul_f32 v[44:45], v[44:45], v[46:47]
	v_pk_fma_f32 v[32:33], v[68:69], v[32:33], 0 op_sel_hi:[1,1,0]
	v_add_f32_e32 v60, 1.0, v60
	v_rcp_f32_e32 v60, v60
; DI float bflo(unsigned w) { return __uint_as_float(w << 16); }
; DI float bfhi(unsigned w) { return __uint_as_float(w & 0xffff0000u); }
; DI float siluf_(float x) { return x * __builtin_amdgcn_rcpf(1.0f + __expf(-x)); }
; DI float wave_sum(float v) { v = row16_sum(v); return (rdlane(v, 0) + rdlane(v, 16)) + (rdlane(v, 32) + rdlane(v, 48)); }
; DI void gdn_unit(const Params& P, bf16_t* proj, const float* gb, int b, int h, LAS unsigned char* lds) {
;     ...
;         for (int w = 0; w < 3; ++w) {
;             const f32x2 (&cw)[4] = cwr[w];
;             const unsigned (&raw)[11] = rawq[w];
;             float o0[8], o1[8];
; #pragma unroll
;             for (int i = 0; i < 8; ++i) {
;                 float a0 = 0.f, a1 = 0.f;
; #pragma unroll
;                 for (int j = 0; j < 4; ++j) { a0 += cw[j][0] * bflo(raw[i + j]); a1 += cw[j][1] * bfhi(raw[i + j]); }
;                 a0 = siluf_(a0); a1 = siluf_(a1);
;                 if (w < 2) {
;                     const float ss = wave_sum(a0 * a0 + a1 * a1);
;                     const float rs = rsqrtf(ss + 1e-6f) * (w == 0 ? 0.08838834764831845f : 1.0f);
;                     a0 *= rs; a1 *= rs;
;                 }
;                 o0[i] = a0; o1[i] = a1;
	v_add_f32_dpp v50, v50, v50 row_half_mirror row_mask:0xf bank_mask:0xf bound_ctrl:1
	v_pk_mul_f32 v[46:47], v[44:45], v[44:45]
	v_pk_fma_f32 v[32:33], v[70:71], v[34:35], v[32:33]
	v_pk_mul_f32 v[60:61], v[52:53], v[60:61]
	v_add_f32_dpp v50, v50, v50 row_mirror row_mask:0xf bank_mask:0xf bound_ctrl:1
	v_pk_mul_f32 v[52:53], v[60:61], v[60:61]
	v_add_f32_e32 v46, v47, v46
	v_add_f32_e32 v52, v53, v52
	v_and_b32_e32 v39, 0xffff0000, v182
	v_add_f32_dpp v46, v46, v46 quad_perm:[1,0,3,2] row_mask:0xf bank_mask:0xf bound_ctrl:1
	v_add_f32_dpp v52, v52, v52 quad_perm:[1,0,3,2] row_mask:0xf bank_mask:0xf bound_ctrl:1
	v_lshlrev_b32_e32 v38, 16, v182
	v_add_f32_dpp v46, v46, v46 quad_perm:[2,3,0,1] row_mask:0xf bank_mask:0xf bound_ctrl:1
	v_add_f32_dpp v52, v52, v52 quad_perm:[2,3,0,1] row_mask:0xf bank_mask:0xf bound_ctrl:1
	v_pk_fma_f32 v[32:33], v[72:73], v[36:37], v[32:33]
	v_add_f32_dpp v46, v46, v46 row_half_mirror row_mask:0xf bank_mask:0xf bound_ctrl:1
	v_add_f32_dpp v52, v52, v52 row_half_mirror row_mask:0xf bank_mask:0xf bound_ctrl:1
	v_pk_fma_f32 v[32:33], v[74:75], v[38:39], v[32:33]
	v_add_f32_dpp v46, v46, v46 row_mirror row_mask:0xf bank_mask:0xf bound_ctrl:1
	v_add_f32_dpp v52, v52, v52 row_mirror row_mask:0xf bank_mask:0xf bound_ctrl:1
	v_mul_f32_e32 v34, 0xbfb8aa3b, v33
	v_readlane_b32 s2, v52, 16
	v_readlane_b32 s3, v52, 48
	v_readlane_b32 s0, v52, 0
	v_readlane_b32 s1, v52, 32
	v_mov_b32_e32 v52, s2
	v_mov_b32_e32 v53, s3
	v_pk_add_f32 v[52:53], s[0:1], v[52:53]
	v_readlane_b32 s2, v50, 16
	v_add_f32_e32 v52, v52, v53
	v_add_f32_e32 v52, 0x358637bd, v52
	s_nop 0
	s_nop 0
	v_readlane_b32 s3, v50, 48
	s_nop 0
	v_rsq_f32_e32 v52, v52
	v_readlane_b32 s0, v50, 0
	v_readlane_b32 s1, v50, 32
	v_mov_b32_e32 v50, s2
	v_mov_b32_e32 v51, s3
	v_pk_add_f32 v[50:51], s[0:1], v[50:51]
	s_nop 0
	v_add_f32_e32 v50, v50, v51
	v_add_f32_e32 v50, 0x358637bd, v50
	s_nop 0
	s_nop 0
	s_nop 0
	v_readlane_b32 s2, v46, 16
	s_nop 0
	v_rsq_f32_e32 v50, v50
	v_readlane_b32 s3, v46, 48
	v_readlane_b32 s0, v46, 0
	v_readlane_b32 s1, v46, 32
	v_mov_b32_e32 v46, s2
	v_mov_b32_e32 v47, s3
	v_pk_add_f32 v[46:47], s[0:1], v[46:47]
	s_nop 0
	v_add_f32_e32 v46, v46, v47
	v_add_f32_e32 v46, 0x358637bd, v46
	s_nop 0
	s_nop 0
	s_nop 0
	v_exp_f32_e32 v34, v34
	s_nop 0
	v_rsq_f32_e32 v46, v46
	v_bfe_u32 v36, v58, 16, 1
	v_add_f32_e32 v34, 1.0, v34
	v_rcp_f32_e32 v35, v34
	s_nop 0
	s_nop 0
	v_mul_f32_e32 v46, 0x3db504f3, v46
	v_mul_f32_e32 v47, v44, v46
	v_mul_f32_e32 v44, 0xbfb8aa3b, v43
	v_exp_f32_e32 v44, v44
	v_mul_f32_e32 v46, v45, v46
	v_mul_f32_e32 v34, 0xbfb8aa3b, v32
	v_exp_f32_e32 v34, v34
	v_add_f32_e32 v44, 1.0, v44
	v_rcp_f32_e32 v45, v44
	v_mul_f32_e32 v44, 0xbfb8aa3b, v42
	v_exp_f32_e32 v44, v44
	v_add_f32_e32 v34, 1.0, v34
	v_rcp_f32_e32 v34, v34
	v_mul_f32_e32 v52, 0x3db504f3, v52
	v_add_f32_e32 v44, 1.0, v44
	v_rcp_f32_e32 v44, v44
	v_pk_mul_f32 v[32:33], v[32:33], v[34:35]
	v_add3_u32 v36, v58, v36, s68
	v_pk_mul_f32 v[34:35], v[32:33], v[32:33]
	v_pk_mul_f32 v[42:43], v[42:43], v[44:45]
	v_add_f32_e32 v34, v35, v34
	v_pk_mul_f32 v[44:45], v[42:43], v[42:43]
	v_mul_f32_e32 v53, v60, v52
	v_add_f32_e32 v44, v45, v44
	v_add_f32_dpp v34, v34, v34 quad_perm:[1,0,3,2] row_mask:0xf bank_mask:0xf bound_ctrl:1
	v_mul_f32_e32 v52, v61, v52
	v_add_f32_dpp v44, v44, v44 quad_perm:[1,0,3,2] row_mask:0xf bank_mask:0xf bound_ctrl:1
	v_add_f32_dpp v34, v34, v34 quad_perm:[2,3,0,1] row_mask:0xf bank_mask:0xf bound_ctrl:1
	v_mul_f32_e32 v50, 0x3db504f3, v50
	v_add_f32_dpp v44, v44, v44 quad_perm:[2,3,0,1] row_mask:0xf bank_mask:0xf bound_ctrl:1
	v_add_f32_dpp v34, v34, v34 row_half_mirror row_mask:0xf bank_mask:0xf bound_ctrl:1
	v_mul_f32_e32 v48, v48, v50
	v_add_f32_dpp v44, v44, v44 row_half_mirror row_mask:0xf bank_mask:0xf bound_ctrl:1
	v_add_f32_dpp v34, v34, v34 row_mirror row_mask:0xf bank_mask:0xf bound_ctrl:1
	v_mul_f32_e32 v49, v49, v50
	v_add_f32_dpp v44, v44, v44 row_mirror row_mask:0xf bank_mask:0xf bound_ctrl:1
	v_and_b32_e32 v50, 0xffff0000, v181
	v_readlane_b32 s2, v44, 16
	v_readlane_b32 s3, v44, 48
	v_readlane_b32 s0, v44, 0
	v_readlane_b32 s1, v44, 32
	v_mov_b32_e32 v44, s2
	v_mov_b32_e32 v45, s3
	v_pk_add_f32 v[44:45], s[0:1], v[44:45]
	v_lshlrev_b32_e32 v60, 16, v180
	v_add_f32_e32 v44, v44, v45
	v_add_f32_e32 v44, 0x358637bd, v44
	s_nop 0
	s_nop 0
	v_lshlrev_b32_e32 v38, 16, v184
	s_nop 0
	v_rsq_f32_e32 v44, v44
	v_lshlrev_b32_e32 v62, 16, v177
	v_mov_b32_e32 v63, v60
	v_lshlrev_b32_e32 v58, 16, v181
	s_nop 0
	s_nop 0
	v_mul_f32_e32 v44, 0x3db504f3, v44
	v_mul_f32_e32 v45, v42, v44
	v_mul_f32_e32 v42, 0xbfb8aa3b, v41
	v_exp_f32_e32 v42, v42
	v_mul_f32_e32 v44, v43, v44
	v_pk_fma_f32 v[62:63], v[98:99], v[62:63], 0 op_sel_hi:[1,1,0]
	v_lshlrev_b32_e32 v61, 16, v183
	v_add_f32_e32 v42, 1.0, v42
	v_rcp_f32_e32 v43, v42
	v_mul_f32_e32 v42, 0xbfb8aa3b, v40
	v_exp_f32_e32 v42, v42
	v_lshlrev_b32_e32 v39, 16, v186
	s_mov_b32 s76, 0x358637bd
	s_mov_b32 s78, 0x45800000
	v_add_f32_e32 v42, 1.0, v42
	v_rcp_f32_e32 v42, v42
	v_lshlrev_b32_e32 v37, 16, v190
	s_mov_b32 s72, 0x358637bd
	s_cmp_eq_u32 s14, 0xf80000
	v_pk_mul_f32 v[40:41], v[40:41], v[42:43]
	s_nop 0
	v_pk_mul_f32 v[42:43], v[40:41], v[40:41]
	s_nop 0
	v_add_f32_e32 v42, v43, v42
	s_nop 1
	v_add_f32_dpp v42, v42, v42 quad_perm:[1,0,3,2] row_mask:0xf bank_mask:0xf bound_ctrl:1
	s_nop 1
	v_add_f32_dpp v42, v42, v42 quad_perm:[2,3,0,1] row_mask:0xf bank_mask:0xf bound_ctrl:1
	s_nop 1
	v_add_f32_dpp v42, v42, v42 row_half_mirror row_mask:0xf bank_mask:0xf bound_ctrl:1
	s_nop 1
	v_add_f32_dpp v42, v42, v42 row_mirror row_mask:0xf bank_mask:0xf bound_ctrl:1
	s_nop 0
	v_readlane_b32 s2, v42, 16
; #define LAS __attribute__((address_space(3)))
; DI unsigned pk2(float lo, float hi) { return f2bf(lo) | (f2bf(hi) << 16); }
; DI float wave_sum(float v) { v = row16_sum(v); return (rdlane(v, 0) + rdlane(v, 16)) + (rdlane(v, 32) + rdlane(v, 48)); }
; DI void gdn_unit(const Params& P, bf16_t* proj, const float* gb, int b, int h, LAS unsigned char* lds) {
;     ...
;                 if (w < 2) {
;                     const float ss = wave_sum(a0 * a0 + a1 * a1);
;                     const float rs = rsqrtf(ss + 1e-6f) * (w == 0 ? 0.08838834764831845f : 1.0f);
;                     a0 *= rs; a1 *= rs;
;                 }
;                 o0[i] = a0; o1[i] = a1;
;             }
;             if (w < 2) {
;                 const int off = (w == 0) ? Q_OFF : K_OFF;
; #pragma unroll
;                 for (int i = 0; i < 8; ++i) *(LAS unsigned*)(lds + off + (wave * 8 + i) * 272 + lane * 4) = pk2(o0[i], o1[i]);
	v_readlane_b32 s3, v42, 48
	v_readlane_b32 s0, v42, 0
	v_readlane_b32 s1, v42, 32
	v_mov_b32_e32 v42, s2
	v_mov_b32_e32 v43, s3
	v_pk_add_f32 v[42:43], s[0:1], v[42:43]
	v_readlane_b32 s2, v34, 16
	v_add_f32_e32 v42, v42, v43
	v_add_f32_e32 v42, 0x358637bd, v42
	s_nop 0
	s_nop 0
	v_readlane_b32 s3, v34, 48
	s_nop 0
	v_rsq_f32_e32 v42, v42
	v_readlane_b32 s0, v34, 0
	v_readlane_b32 s1, v34, 32
	v_mov_b32_e32 v34, s2
	v_mov_b32_e32 v35, s3
	v_pk_add_f32 v[34:35], s[0:1], v[34:35]
	s_nop 0
	v_add_f32_e32 v34, v34, v35
	v_add_f32_e32 v34, 0x358637bd, v34
	s_nop 0
	s_nop 0
	s_nop 0
	v_mul_f32_e32 v42, 0x3db504f3, v42
	s_nop 0
	v_rsq_f32_e32 v34, v34
	v_mul_f32_e32 v40, v40, v42
	v_mul_f32_e32 v41, v41, v42
	v_and_b32_e32 v42, 0xffff0000, v184
	s_nop 0
	v_mul_f32_e32 v34, 0x3db504f3, v34
	v_mul_f32_e32 v32, v32, v34
	v_mul_f32_e32 v33, v33, v34
	s_nop 0
	v_cvt_pk_bf16_f32 v34, v57, v56
	v_cvt_pk_bf16_f32 v35, v59, v59
	v_lshrrev_b32_e32 v35, 16, v35
	v_add_u32_e32 v56, s92, v54
	v_and_or_b32 v35, v36, s39, v35
	ds_write2_b32 v56, v34, v35 offset1:68
	v_cvt_pk_bf16_f32 v34, v53, v52
	v_cvt_pk_bf16_f32 v35, v48, v49
	ds_write2_b32 v56, v34, v35 offset0:136 offset1:204
	v_cvt_pk_bf16_f32 v34, v47, v46
	v_cvt_pk_bf16_f32 v35, v45, v44
	v_add_u32_e32 v36, 0x400, v56
	ds_write2_b32 v36, v34, v35 offset0:16 offset1:84
	v_cvt_pk_bf16_f32 v34, v40, v41
	v_cvt_pk_bf16_f32 v32, v32, v33
	ds_write2_b32 v36, v34, v32 offset0:152 offset1:220
	v_and_b32_e32 v32, 0xffff0000, v177
	v_and_b32_e32 v48, 0xffff0000, v183
	v_mov_b32_e32 v33, v42
	v_and_b32_e32 v49, 0xffff0000, v186
	v_pk_fma_f32 v[32:33], v[76:77], v[32:33], 0 op_sel_hi:[1,1,0]
	v_mov_b32_e32 v51, v48
	v_and_b32_e32 v52, 0xffff0000, v180
	v_mov_b32_e32 v53, v49
	v_pk_fma_f32 v[32:33], v[92:93], v[50:51], v[32:33]
	v_and_b32_e32 v43, 0xffff0000, v185
	v_pk_fma_f32 v[32:33], v[94:95], v[52:53], v[32:33]
	v_mov_b32_e32 v51, v52
	v_pk_fma_f32 v[32:33], v[96:97], v[42:43], v[32:33]
	v_pk_fma_f32 v[50:51], v[76:77], v[50:51], 0 op_sel_hi:[1,1,0]
	v_mul_f32_e32 v34, 0xbfb8aa3b, v32
	v_exp_f32_e32 v34, v34
	v_mov_b32_e32 v53, v42
	v_mov_b32_e32 v64, v42
	v_mov_b32_e32 v65, v48
	v_add_f32_e32 v34, 1.0, v34
	v_rcp_f32_e32 v110, v34
	v_mul_f32_e32 v34, 0xbfb8aa3b, v33
	v_exp_f32_e32 v34, v34
	v_pk_fma_f32 v[50:51], v[92:93], v[52:53], v[50:51]
	v_mov_b32_e32 v59, v38
	v_pk_fma_f32 v[50:51], v[94:95], v[64:65], v[50:51]
	v_add_f32_e32 v34, 1.0, v34
	v_pk_fma_f32 v[50:51], v[96:97], v[48:49], v[50:51]
	v_rcp_f32_e32 v111, v34
	v_mul_f32_e32 v34, 0xbfb8aa3b, v50
	v_exp_f32_e32 v34, v34
	v_pk_fma_f32 v[62:63], v[78:79], v[58:59], v[62:63]
	v_pk_fma_f32 v[58:59], v[98:99], v[58:59], 0 op_sel_hi:[1,1,0]
	v_pk_fma_f32 v[62:63], v[80:81], v[60:61], v[62:63]
	v_add_f32_e32 v34, 1.0, v34
	v_rcp_f32_e32 v52, v34
	v_mul_f32_e32 v34, 0xbfb8aa3b, v51
	v_exp_f32_e32 v34, v34
	v_pk_fma_f32 v[62:63], v[82:83], v[38:39], v[62:63]
	v_pk_fma_f32 v[58:59], v[78:79], v[60:61], v[58:59]
	v_mul_f32_e32 v57, 0xbfb8aa3b, v62
	v_exp_f32_e32 v57, v57
	v_add_f32_e32 v34, 1.0, v34
	v_lshlrev_b32_e32 v35, 16, v185
	v_rcp_f32_e32 v53, v34
	v_mov_b32_e32 v34, v61
	v_pk_fma_f32 v[58:59], v[80:81], v[38:39], v[58:59]
	v_add_f32_e32 v57, 1.0, v57
	v_pk_fma_f32 v[58:59], v[82:83], v[34:35], v[58:59]
	v_rcp_f32_e32 v64, v57
	v_mul_f32_e32 v38, 0xbfb8aa3b, v58
	v_mul_f32_e32 v57, 0xbfb8aa3b, v63
	v_exp_f32_e32 v38, v38
	v_exp_f32_e32 v57, v57
	v_pk_mul_f32 v[32:33], v[32:33], v[110:111]
	v_pk_mul_f32 v[52:53], v[50:51], v[52:53]
	v_add_f32_e32 v38, 1.0, v38
	v_add_f32_e32 v57, 1.0, v57
	v_rcp_f32_e32 v60, v38
	v_mul_f32_e32 v38, 0xbfb8aa3b, v59
	v_rcp_f32_e32 v65, v57
	v_exp_f32_e32 v38, v38
	v_mov_b32_e32 v112, v33
	v_mov_b32_e32 v110, v53
	v_pk_mul_f32 v[62:63], v[62:63], v[64:65]
	v_add_f32_e32 v38, 1.0, v38
	v_mov_b32_e32 v64, v32
	v_mov_b32_e32 v65, v62
	v_rcp_f32_e32 v61, v38
	v_pk_mul_f32 v[64:65], v[64:65], v[64:65]
	v_mov_b32_e32 v111, v63
	v_add_f32_e32 v38, v64, v65
	v_pk_mul_f32 v[58:59], v[58:59], v[60:61]
	v_mov_b32_e32 v60, v52
	v_add_f32_dpp v38, v38, v38 quad_perm:[1,0,3,2] row_mask:0xf bank_mask:0xf bound_ctrl:1
	v_mov_b32_e32 v113, v59
	v_pk_mul_f32 v[112:113], v[112:113], v[112:113]
	v_add_f32_dpp v38, v38, v38 quad_perm:[2,3,0,1] row_mask:0xf bank_mask:0xf bound_ctrl:1
	v_mov_b32_e32 v61, v58
	v_pk_mul_f32 v[60:61], v[60:61], v[60:61]
	v_add_f32_dpp v38, v38, v38 row_half_mirror row_mask:0xf bank_mask:0xf bound_ctrl:1
	v_pk_mul_f32 v[110:111], v[110:111], v[110:111]
	v_and_b32_e32 v44, 0xffff0000, v187
	v_add_f32_dpp v38, v38, v38 row_mirror row_mask:0xf bank_mask:0xf bound_ctrl:1
	v_and_b32_e32 v47, 0xffff0000, v190
	v_readlane_b32 s0, v38, 0
	v_readlane_b32 s3, v38, 16
	v_readlane_b32 s2, v38, 32
	v_readlane_b32 s16, v38, 48
	v_add_f32_e32 v38, v112, v113
	v_mov_b32_e32 v64, s3
	v_mov_b32_e32 v112, s16
	v_add_f32_dpp v38, v38, v38 quad_perm:[1,0,3,2] row_mask:0xf bank_mask:0xf bound_ctrl:1
	v_and_b32_e32 v46, 0xffff0000, v188
	v_mov_b32_e32 v50, v49
	v_add_f32_dpp v38, v38, v38 quad_perm:[2,3,0,1] row_mask:0xf bank_mask:0xf bound_ctrl:1
	v_and_b32_e32 v45, 0xffff0000, v189
	v_mov_b32_e32 v51, v43
	v_add_f32_dpp v38, v38, v38 row_half_mirror row_mask:0xf bank_mask:0xf bound_ctrl:1
	v_lshlrev_b32_e32 v36, 16, v187
	v_lshlrev_b32_e32 v40, 16, v188
	v_add_f32_dpp v38, v38, v38 row_mirror row_mask:0xf bank_mask:0xf bound_ctrl:1
	v_lshlrev_b32_e32 v41, 16, v189
	v_readlane_b32 s17, v38, 16
	v_readlane_b32 s1, v38, 0
	v_readlane_b32 s3, v38, 32
	v_mov_b32_e32 v65, s17
	v_pk_add_f32 v[64:65], s[0:1], v[64:65]
	v_readlane_b32 s0, v38, 48
	s_nop 1
	v_mov_b32_e32 v113, s0
	v_pk_add_f32 v[112:113], s[2:3], v[112:113]
	s_nop 0
; #define LAS __attribute__((address_space(3)))
; DI unsigned pk2(float lo, float hi) { return f2bf(lo) | (f2bf(hi) << 16); }
; DI float bflo(unsigned w) { return __uint_as_float(w << 16); }
; DI float bfhi(unsigned w) { return __uint_as_float(w & 0xffff0000u); }
; DI float siluf_(float x) { return x * __builtin_amdgcn_rcpf(1.0f + __expf(-x)); }
; DI float wave_sum(float v) { v = row16_sum(v); return (rdlane(v, 0) + rdlane(v, 16)) + (rdlane(v, 32) + rdlane(v, 48)); }
; DI void gdn_unit(const Params& P, bf16_t* proj, const float* gb, int b, int h, LAS unsigned char* lds) {
;     ...
;             for (int i = 0; i < 8; ++i) {
;                 float a0 = 0.f, a1 = 0.f;
; #pragma unroll
;                 for (int j = 0; j < 4; ++j) { a0 += cw[j][0] * bflo(raw[i + j]); a1 += cw[j][1] * bfhi(raw[i + j]); }
;                 a0 = siluf_(a0); a1 = siluf_(a1);
;                 if (w < 2) {
;                     const float ss = wave_sum(a0 * a0 + a1 * a1);
;                     const float rs = rsqrtf(ss + 1e-6f) * (w == 0 ? 0.08838834764831845f : 1.0f);
;                     a0 *= rs; a1 *= rs;
;                 }
;                 o0[i] = a0; o1[i] = a1;
;             }
;             if (w < 2) {
;                 const int off = (w == 0) ? Q_OFF : K_OFF;
; #pragma unroll
;                 for (int i = 0; i < 8; ++i) *(LAS unsigned*)(lds + off + (wave * 8 + i) * 272 + lane * 4) = pk2(o0[i], o1[i]);
	v_pk_add_f32 v[64:65], v[64:65], v[112:113]
	s_nop 0
	v_pk_add_f32 v[64:65], v[64:65], s[76:77] op_sel_hi:[1,0]
	s_nop 0
	v_mul_f32_e32 v38, 0x4b800000, v64
	v_cmp_gt_f32_e64 s[0:1], s26, v64
	v_cmp_gt_f32_e32 vcc, s26, v65
	s_nop 0
	v_cndmask_b32_e64 v38, v64, v38, s[0:1]
	v_rsq_f32_e32 v64, v38
	v_mul_f32_e32 v38, 0x4b800000, v65
	v_cndmask_b32_e32 v38, v65, v38, vcc
	v_rsq_f32_e32 v65, v38
	v_add_f32_e32 v38, v60, v61
	v_pk_mul_f32 v[112:113], v[64:65], s[78:79] op_sel_hi:[1,0]
	s_nop 0
	v_add_f32_dpp v38, v38, v38 quad_perm:[1,0,3,2] row_mask:0xf bank_mask:0xf bound_ctrl:1
	v_cndmask_b32_e64 v64, v64, v112, s[0:1]
	v_cndmask_b32_e32 v65, v65, v113, vcc
	v_add_f32_dpp v38, v38, v38 quad_perm:[2,3,0,1] row_mask:0xf bank_mask:0xf bound_ctrl:1
	v_pk_mul_f32 v[32:33], v[32:33], v[64:65]
	s_nop 0
	v_add_f32_dpp v38, v38, v38 row_half_mirror row_mask:0xf bank_mask:0xf bound_ctrl:1
	v_and_b32_sdwa v57, v32, v166 dst_sel:DWORD dst_unused:UNUSED_PAD src0_sel:WORD_1 src1_sel:DWORD
	v_add3_u32 v32, v32, v57, s68
	v_add_f32_dpp v38, v38, v38 row_mirror row_mask:0xf bank_mask:0xf bound_ctrl:1
	s_nop 0
	v_readlane_b32 s0, v38, 0
	v_readlane_b32 s3, v38, 16
	v_readlane_b32 s2, v38, 32
	v_readlane_b32 s16, v38, 48
	v_add_f32_e32 v38, v110, v111
	v_mov_b32_e32 v60, s3
	v_mov_b32_e32 v110, s16
	v_add_f32_dpp v38, v38, v38 quad_perm:[1,0,3,2] row_mask:0xf bank_mask:0xf bound_ctrl:1
	s_nop 1
	v_add_f32_dpp v38, v38, v38 quad_perm:[2,3,0,1] row_mask:0xf bank_mask:0xf bound_ctrl:1
	s_nop 1
	v_add_f32_dpp v38, v38, v38 row_half_mirror row_mask:0xf bank_mask:0xf bound_ctrl:1
	s_nop 1
	v_add_f32_dpp v38, v38, v38 row_mirror row_mask:0xf bank_mask:0xf bound_ctrl:1
	s_nop 0
	v_readlane_b32 s17, v38, 16
	v_readlane_b32 s1, v38, 0
	v_readlane_b32 s3, v38, 32
	v_mov_b32_e32 v61, s17
	v_pk_add_f32 v[60:61], s[0:1], v[60:61]
	v_readlane_b32 s0, v38, 48
	s_nop 1
	v_mov_b32_e32 v111, s0
	v_pk_add_f32 v[110:111], s[2:3], v[110:111]
	s_nop 0
	v_pk_add_f32 v[60:61], v[60:61], v[110:111]
	s_nop 0
	v_pk_add_f32 v[60:61], v[60:61], s[76:77] op_sel_hi:[1,0]
	s_nop 0
	v_mul_f32_e32 v38, 0x4b800000, v60
	v_cmp_gt_f32_e64 s[0:1], s26, v60
	v_cmp_gt_f32_e32 vcc, s26, v61
	s_nop 0
	v_cndmask_b32_e64 v38, v60, v38, s[0:1]
	v_rsq_f32_e32 v60, v38
	v_mul_f32_e32 v38, 0x4b800000, v61
	v_cndmask_b32_e32 v38, v61, v38, vcc
	v_rsq_f32_e32 v61, v38
	s_nop 0
	v_cvt_pk_bf16_f32 v33, v33, v33
	v_and_b32_e32 v33, 0xffff0000, v33
	v_pk_mul_f32 v[110:111], v[60:61], s[78:79] op_sel_hi:[1,0]
	s_nop 0
	v_cndmask_b32_e32 v61, v61, v111, vcc
	v_cndmask_b32_e64 v60, v60, v110, s[0:1]
	v_mov_b32_e32 v111, v61
	v_pk_mul_f32 v[52:53], v[52:53], v[60:61]
	v_mov_b32_e32 v61, v65
	v_mov_b32_e32 v110, v64
	v_pk_mul_f32 v[58:59], v[58:59], v[60:61]
	v_pk_mul_f32 v[62:63], v[62:63], v[110:111]
	v_and_b32_sdwa v61, v59, v166 dst_sel:DWORD dst_unused:UNUSED_PAD src0_sel:WORD_1 src1_sel:DWORD
	v_add3_u32 v61, v59, v61, s68
	v_cvt_pk_bf16_f32 v57, v62, v62
	v_and_b32_sdwa v62, v58, v166 dst_sel:DWORD dst_unused:UNUSED_PAD src0_sel:WORD_1 src1_sel:DWORD
	v_cvt_pk_bf16_f32 v52, v52, v52
	v_cvt_pk_bf16_f32 v38, v63, v63
	v_lshrrev_b32_e32 v57, 16, v57
	v_add3_u32 v62, v58, v62, s68
	v_and_b32_sdwa v58, v53, v166 dst_sel:DWORD dst_unused:UNUSED_PAD src0_sel:WORD_1 src1_sel:DWORD
	v_and_b32_e32 v52, 0xffff0000, v52
	v_lshrrev_b32_e32 v60, 16, v38
	v_and_or_b32 v38, v32, s39, v57
	v_add3_u32 v53, v53, v58, s68
	v_or_b32_sdwa v58, v52, v62 dst_sel:DWORD dst_unused:UNUSED_PAD src0_sel:DWORD src1_sel:WORD_1
	v_add_u32_e32 v59, 0x4400, v56
	ds_write2_b32 v59, v38, v58 offset1:68
	v_and_or_b32 v38, v53, s39, v60
	v_or_b32_sdwa v58, v33, v61 dst_sel:DWORD dst_unused:UNUSED_PAD src0_sel:DWORD src1_sel:WORD_1
	ds_write2_b32 v59, v38, v58 offset0:136 offset1:204
	v_mov_b32_e32 v58, v48
	v_mov_b32_e32 v59, v44
	v_pk_fma_f32 v[58:59], v[76:77], v[58:59], 0 op_sel_hi:[1,1,0]
	v_pk_mov_b32 v[48:49], v[48:49], v[46:47] op_sel:[1,0]
	v_or_b32_sdwa v32, v32, v52 dst_sel:DWORD dst_unused:UNUSED_PAD src0_sel:WORD_1 src1_sel:DWORD
	v_pk_fma_f32 v[48:49], v[92:93], v[48:49], v[58:59]
	v_mov_b32_e32 v58, v43
	v_mov_b32_e32 v59, v47
	v_pk_fma_f32 v[48:49], v[94:95], v[58:59], v[48:49]
	v_mov_b32_e32 v52, v44
	v_pk_fma_f32 v[48:49], v[96:97], v[44:45], v[48:49]
	v_pk_mov_b32 v[42:43], v[42:43], v[44:45] op_sel:[1,0]
	v_mul_f32_e32 v38, 0xbfb8aa3b, v49
	v_exp_f32_e32 v38, v38
	v_pk_fma_f32 v[44:45], v[76:77], v[50:51], 0 op_sel_hi:[1,1,0]
	v_or_b32_sdwa v33, v33, v53 dst_sel:DWORD dst_unused:UNUSED_PAD src0_sel:DWORD src1_sel:WORD_1
	v_mov_b32_e32 v53, v46
	v_add_f32_e32 v38, 1.0, v38
	v_rcp_f32_e32 v59, v38
	v_mul_f32_e32 v38, 0xbfb8aa3b, v48
	v_exp_f32_e32 v38, v38
	v_pk_fma_f32 v[42:43], v[92:93], v[42:43], v[44:45]
	v_lshlrev_b32_e32 v50, 16, v195
	v_pk_fma_f32 v[42:43], v[94:95], v[52:53], v[42:43]
	v_add_f32_e32 v38, 1.0, v38
	v_pk_fma_f32 v[42:43], v[96:97], v[46:47], v[42:43]
	v_rcp_f32_e32 v58, v38
	v_mul_f32_e32 v38, 0xbfb8aa3b, v42
	v_exp_f32_e32 v38, v38
	v_pk_mov_b32 v[46:47], v[34:35], v[40:41] op_sel:[1,0]
	v_pk_fma_f32 v[34:35], v[98:99], v[34:35], 0 op_sel_hi:[1,1,0]
	v_pk_mul_f32 v[48:49], v[48:49], v[58:59]
	v_add_f32_e32 v38, 1.0, v38
	v_rcp_f32_e32 v44, v38
	v_mul_f32_e32 v38, 0xbfb8aa3b, v43
	v_exp_f32_e32 v38, v38
	v_lshlrev_b32_e32 v51, 16, v197
	v_lshlrev_b32_e32 v53, 16, v196
	v_add_f32_e32 v38, 1.0, v38
	v_rcp_f32_e32 v45, v38
	v_pk_mov_b32 v[38:39], v[38:39], v[36:37] op_sel:[1,0]
	v_pk_mul_f32 v[42:43], v[42:43], v[44:45]
	v_pk_fma_f32 v[44:45], v[98:99], v[38:39], 0 op_sel_hi:[1,1,0]
	v_pk_fma_f32 v[34:35], v[78:79], v[38:39], v[34:35]
	v_pk_fma_f32 v[44:45], v[78:79], v[46:47], v[44:45]
; #define LAS __attribute__((address_space(3)))
; DI unsigned pk2(float lo, float hi) { return f2bf(lo) | (f2bf(hi) << 16); }
; DI float bflo(unsigned w) { return __uint_as_float(w << 16); }
; DI float bfhi(unsigned w) { return __uint_as_float(w & 0xffff0000u); }
; DI float siluf_(float x) { return x * __builtin_amdgcn_rcpf(1.0f + __expf(-x)); }
; DI float wave_sum(float v) { v = row16_sum(v); return (rdlane(v, 0) + rdlane(v, 16)) + (rdlane(v, 32) + rdlane(v, 48)); }
; DI void gdn_unit(const Params& P, bf16_t* proj, const float* gb, int b, int h, LAS unsigned char* lds) {
;     ...
;             for (int i = 0; i < 8; ++i) {
;                 float a0 = 0.f, a1 = 0.f;
; #pragma unroll
;                 for (int j = 0; j < 4; ++j) { a0 += cw[j][0] * bflo(raw[i + j]); a1 += cw[j][1] * bfhi(raw[i + j]); }
;                 a0 = siluf_(a0); a1 = siluf_(a1);
;                 if (w < 2) {
;                     const float ss = wave_sum(a0 * a0 + a1 * a1);
;                     const float rs = rsqrtf(ss + 1e-6f) * (w == 0 ? 0.08838834764831845f : 1.0f);
;                     a0 *= rs; a1 *= rs;
;                 }
;                 o0[i] = a0; o1[i] = a1;
;             }
;             if (w < 2) {
;                 const int off = (w == 0) ? Q_OFF : K_OFF;
; #pragma unroll
;                 for (int i = 0; i < 8; ++i) *(LAS unsigned*)(lds + off + (wave * 8 + i) * 272 + lane * 4) = pk2(o0[i], o1[i]);
	v_pk_fma_f32 v[34:35], v[80:81], v[46:47], v[34:35]
	v_pk_fma_f32 v[44:45], v[80:81], v[36:37], v[44:45]
	v_pk_fma_f32 v[34:35], v[82:83], v[36:37], v[34:35]
	v_pk_fma_f32 v[40:41], v[82:83], v[40:41], v[44:45]
	v_mul_f32_e32 v36, 0xbfb8aa3b, v34
	v_mul_f32_e32 v44, 0xbfb8aa3b, v41
	v_exp_f32_e32 v44, v44
	v_mul_f32_e32 v37, 0xbfb8aa3b, v35
	v_exp_f32_e32 v36, v36
	v_exp_f32_e32 v37, v37
	v_add_f32_e32 v44, 1.0, v44
	v_rcp_f32_e32 v45, v44
	v_mul_f32_e32 v44, 0xbfb8aa3b, v40
	v_exp_f32_e32 v44, v44
	v_add_f32_e32 v36, 1.0, v36
	v_add_f32_e32 v37, 1.0, v37
	v_rcp_f32_e32 v36, v36
	v_add_f32_e32 v44, 1.0, v44
	v_rcp_f32_e32 v44, v44
	v_rcp_f32_e32 v37, v37
	v_mov_b32_e32 v38, v42
	v_mov_b32_e32 v46, v43
	v_pk_mul_f32 v[40:41], v[40:41], v[44:45]
	v_mov_b32_e32 v44, v49
	v_mov_b32_e32 v45, v41
	v_pk_mul_f32 v[34:35], v[34:35], v[36:37]
	v_pk_mul_f32 v[44:45], v[44:45], v[44:45]
	v_mov_b32_e32 v36, v48
	v_mov_b32_e32 v37, v34
	v_pk_mul_f32 v[36:37], v[36:37], v[36:37]
	v_add_f32_e32 v44, v44, v45
	v_add_f32_e32 v36, v36, v37
	v_mov_b32_e32 v39, v40
	v_add_f32_dpp v44, v44, v44 quad_perm:[1,0,3,2] row_mask:0xf bank_mask:0xf bound_ctrl:1
	v_add_f32_dpp v36, v36, v36 quad_perm:[1,0,3,2] row_mask:0xf bank_mask:0xf bound_ctrl:1
	v_pk_mul_f32 v[38:39], v[38:39], v[38:39]
	v_add_f32_dpp v44, v44, v44 quad_perm:[2,3,0,1] row_mask:0xf bank_mask:0xf bound_ctrl:1
	v_add_f32_dpp v36, v36, v36 quad_perm:[2,3,0,1] row_mask:0xf bank_mask:0xf bound_ctrl:1
	v_add_f32_e32 v38, v38, v39
	v_add_f32_dpp v44, v44, v44 row_half_mirror row_mask:0xf bank_mask:0xf bound_ctrl:1
	v_add_f32_dpp v36, v36, v36 row_half_mirror row_mask:0xf bank_mask:0xf bound_ctrl:1
	v_add_f32_dpp v38, v38, v38 quad_perm:[1,0,3,2] row_mask:0xf bank_mask:0xf bound_ctrl:1
	v_add_f32_dpp v44, v44, v44 row_mirror row_mask:0xf bank_mask:0xf bound_ctrl:1
	v_mov_b32_e32 v47, v35
	v_readlane_b32 s1, v44, 0
	v_readlane_b32 s2, v44, 16
	v_readlane_b32 s3, v44, 32
	v_readlane_b32 s16, v44, 48
	v_add_f32_dpp v44, v36, v36 row_mirror row_mask:0xf bank_mask:0xf bound_ctrl:1
	v_mov_b32_e32 v37, s2
	v_readlane_b32 s17, v44, 16
	v_readlane_b32 s0, v44, 0
	v_readlane_b32 s2, v44, 32
	v_mov_b32_e32 v36, s17
	v_pk_add_f32 v[36:37], s[0:1], v[36:37]
	v_readlane_b32 s0, v44, 48
	v_mov_b32_e32 v45, s16
	v_add_f32_dpp v38, v38, v38 quad_perm:[2,3,0,1] row_mask:0xf bank_mask:0xf bound_ctrl:1
	v_mov_b32_e32 v44, s0
	v_pk_add_f32 v[44:45], s[2:3], v[44:45]
	v_add_f32_dpp v38, v38, v38 row_half_mirror row_mask:0xf bank_mask:0xf bound_ctrl:1
	v_pk_add_f32 v[36:37], v[36:37], v[44:45]
	v_pk_mul_f32 v[46:47], v[46:47], v[46:47]
	v_pk_add_f32 v[36:37], v[36:37], s[76:77] op_sel_hi:[1,0]
	v_add_f32_dpp v38, v38, v38 row_mirror row_mask:0xf bank_mask:0xf bound_ctrl:1
	v_mul_f32_e32 v44, 0x4b800000, v37
	v_cmp_gt_f32_e64 s[0:1], s26, v37
	v_cmp_gt_f32_e32 vcc, s26, v36
	v_readlane_b32 s3, v38, 16
	v_cndmask_b32_e64 v37, v37, v44, s[0:1]
	v_mul_f32_e32 v44, 0x4b800000, v36
	v_cndmask_b32_e32 v36, v36, v44, vcc
	v_rsq_f32_e32 v37, v37
	v_rsq_f32_e32 v36, v36
	v_readlane_b32 s2, v38, 32
	v_readlane_b32 s16, v38, 48
	v_pk_mul_f32 v[44:45], v[36:37], s[78:79] op_sel_hi:[1,0]
	s_nop 0
	v_cndmask_b32_e64 v37, v37, v45, s[0:1]
	v_readlane_b32 s0, v38, 0
	v_add_f32_e32 v38, v46, v47
	v_cndmask_b32_e32 v36, v36, v44, vcc
	v_mov_b32_e32 v47, v50
	v_add_f32_dpp v38, v38, v38 quad_perm:[1,0,3,2] row_mask:0xf bank_mask:0xf bound_ctrl:1
	s_nop 1
	v_add_f32_dpp v38, v38, v38 quad_perm:[2,3,0,1] row_mask:0xf bank_mask:0xf bound_ctrl:1
	s_nop 1
	v_add_f32_dpp v38, v38, v38 row_half_mirror row_mask:0xf bank_mask:0xf bound_ctrl:1
	s_nop 1
	v_add_f32_dpp v44, v38, v38 row_mirror row_mask:0xf bank_mask:0xf bound_ctrl:1
	v_mov_b32_e32 v38, s3
	v_readlane_b32 s17, v44, 16
	v_readlane_b32 s1, v44, 0
	v_readlane_b32 s3, v44, 32
	v_mov_b32_e32 v39, s17
	v_pk_add_f32 v[38:39], s[0:1], v[38:39]
	v_readlane_b32 s0, v44, 48
	v_mov_b32_e32 v44, s16
	s_nop 0
	v_mov_b32_e32 v45, s0
	v_pk_add_f32 v[44:45], s[2:3], v[44:45]
	s_nop 0
	v_pk_add_f32 v[38:39], v[38:39], v[44:45]
	s_nop 0
	v_pk_add_f32 v[38:39], v[38:39], s[76:77] op_sel_hi:[1,0]
	s_nop 0
	v_mul_f32_e32 v44, 0x4b800000, v38
	v_cmp_gt_f32_e64 s[0:1], s26, v38
	v_cmp_gt_f32_e32 vcc, s26, v39
	s_nop 0
	v_cndmask_b32_e64 v38, v38, v44, s[0:1]
	v_mul_f32_e32 v44, 0x4b800000, v39
	v_cndmask_b32_e32 v39, v39, v44, vcc
	v_rsq_f32_e32 v38, v38
	v_rsq_f32_e32 v39, v39
	s_nop 0
	v_pk_mul_f32 v[44:45], v[38:39], s[78:79] op_sel_hi:[1,0]
	s_nop 0
	v_cndmask_b32_e64 v38, v38, v44, s[0:1]
	v_cndmask_b32_e32 v39, v39, v45, vcc
	v_mov_b32_e32 v44, v38
	v_mov_b32_e32 v45, v37
	v_pk_mul_f32 v[40:41], v[40:41], v[44:45]
	s_nop 0
	v_and_b32_sdwa v44, v41, v166 dst_sel:DWORD dst_unused:UNUSED_PAD src0_sel:WORD_1 src1_sel:DWORD
	v_and_b32_sdwa v45, v40, v166 dst_sel:DWORD dst_unused:UNUSED_PAD src0_sel:WORD_1 src1_sel:DWORD
	v_add3_u32 v45, v40, v45, s68
	v_add3_u32 v44, v41, v44, s68
	v_pk_mul_f32 v[40:41], v[48:49], v[36:37]
	v_lshlrev_b32_e32 v48, 16, v193
	v_cvt_pk_bf16_f32 v37, v41, v41
	v_and_b32_e32 v41, 0xffff0000, v37
	v_mov_b32_e32 v37, v39
	v_pk_mul_f32 v[34:35], v[34:35], v[36:37]
	v_pk_mul_f32 v[36:37], v[42:43], v[38:39]
	v_and_b32_sdwa v46, v40, v166 dst_sel:DWORD dst_unused:UNUSED_PAD src0_sel:WORD_1 src1_sel:DWORD
	v_cvt_pk_bf16_f32 v34, v34, v34
	v_cvt_pk_bf16_f32 v36, v36, v36
	v_add3_u32 v40, v40, v46, s68
	v_cvt_pk_bf16_f32 v35, v35, v35
	v_lshrrev_b32_e32 v34, 16, v34
	v_and_b32_sdwa v39, v37, v166 dst_sel:DWORD dst_unused:UNUSED_PAD src0_sel:WORD_1 src1_sel:DWORD
	v_and_b32_e32 v42, 0xffff0000, v36
	v_lshrrev_b32_e32 v35, 16, v35
	v_and_or_b32 v38, v40, s39, v34
	v_add3_u32 v43, v37, v39, s68
; #define LAS __attribute__((address_space(3)))
; DI unsigned pk2(float lo, float hi) { return f2bf(lo) | (f2bf(hi) << 16); }
; DI float bflo(unsigned w) { return __uint_as_float(w << 16); }
; DI float bfhi(unsigned w) { return __uint_as_float(w & 0xffff0000u); }
; DI float siluf_(float x) { return x * __builtin_amdgcn_rcpf(1.0f + __expf(-x)); }
; DI float wave_sum(float v) { v = row16_sum(v); return (rdlane(v, 0) + rdlane(v, 16)) + (rdlane(v, 32) + rdlane(v, 48)); }
; DI void gdn_unit(const Params& P, bf16_t* proj, const float* gb, int b, int h, LAS unsigned char* lds) {
;     ...
;         for (int w = 0; w < 3; ++w) {
;             const f32x2 (&cw)[4] = cwr[w];
;             const unsigned (&raw)[11] = rawq[w];
;             float o0[8], o1[8];
; #pragma unroll
;             for (int i = 0; i < 8; ++i) {
;                 float a0 = 0.f, a1 = 0.f;
; #pragma unroll
;                 for (int j = 0; j < 4; ++j) { a0 += cw[j][0] * bflo(raw[i + j]); a1 += cw[j][1] * bfhi(raw[i + j]); }
;                 a0 = siluf_(a0); a1 = siluf_(a1);
;                 if (w < 2) {
;                     const float ss = wave_sum(a0 * a0 + a1 * a1);
;                     const float rs = rsqrtf(ss + 1e-6f) * (w == 0 ? 0.08838834764831845f : 1.0f);
;                     a0 *= rs; a1 *= rs;
;                 }
;                 o0[i] = a0; o1[i] = a1;
;             }
;             if (w < 2) {
;                 const int off = (w == 0) ? Q_OFF : K_OFF;
; #pragma unroll
;                 for (int i = 0; i < 8; ++i) *(LAS unsigned*)(lds + off + (wave * 8 + i) * 272 + lane * 4) = pk2(o0[i], o1[i]);
;             }
;             if (w >= 1) {
;                 const int off = (w == 1) ? KT_OFF : VT_OFF;
;                 u32x4 w0, w1;
;                 w0.x = pk2(o0[0], o0[1]); w0.y = pk2(o0[2], o0[3]); w0.z = pk2(o0[4], o0[5]); w0.w = pk2(o0[6], o0[7]);
;                 w1.x = pk2(o1[0], o1[1]); w1.y = pk2(o1[2], o1[3]); w1.z = pk2(o1[4], o1[5]); w1.w = pk2(o1[6], o1[7]);
;                 *(LAS u32x4*)(lds + off + (2 * lane) * 144 + wave * 16) = w0;
;                 *(LAS u32x4*)(lds + off + (2 * lane + 1) * 144 + wave * 16) = w1;
;             }
	v_or_b32_sdwa v36, v42, v45 dst_sel:DWORD dst_unused:UNUSED_PAD src0_sel:DWORD src1_sel:WORD_1
	v_add_u32_e32 v37, 0x4800, v56
	v_or_b32_sdwa v46, v41, v44 dst_sel:DWORD dst_unused:UNUSED_PAD src0_sel:DWORD src1_sel:WORD_1
	ds_write2_b32 v37, v38, v36 offset0:16 offset1:84
	v_and_or_b32 v36, v43, s39, v35
	ds_write2_b32 v37, v36, v46 offset0:152 offset1:220
	v_lshlrev_b32_e32 v46, 16, v191
	v_lshlrev_b32_e32 v49, 16, v194
	v_pk_fma_f32 v[46:47], v[84:85], v[46:47], 0 op_sel_hi:[1,1,0]
	v_mov_b32_e32 v52, v49
	v_pk_fma_f32 v[46:47], v[86:87], v[48:49], v[46:47]
	v_and_or_b32 v39, v44, s39, v35
	v_pk_fma_f32 v[46:47], v[88:89], v[50:51], v[46:47]
	v_or_b32_sdwa v35, v41, v43 dst_sel:DWORD dst_unused:UNUSED_PAD src0_sel:DWORD src1_sel:WORD_1
	v_pk_fma_f32 v[46:47], v[90:91], v[52:53], v[46:47]
	v_pk_fma_f32 v[48:49], v[84:85], v[48:49], 0 op_sel_hi:[1,1,0]
	v_mul_f32_e32 v41, 0xbfb8aa3b, v46
	v_exp_f32_e32 v41, v41
	v_pk_fma_f32 v[48:49], v[86:87], v[50:51], v[48:49]
	v_and_or_b32 v36, v62, s39, v57
	v_lshlrev_b32_e32 v57, 16, v198
	v_mov_b32_e32 v56, v51
	v_pk_fma_f32 v[48:49], v[88:89], v[52:53], v[48:49]
	v_add_f32_e32 v41, 1.0, v41
	v_pk_fma_f32 v[48:49], v[90:91], v[56:57], v[48:49]
	v_rcp_f32_e32 v58, v41
	v_mul_f32_e32 v41, 0xbfb8aa3b, v48
	v_exp_f32_e32 v41, v41
	v_add3_u32 v62, v54, v55, s4
	v_lshlrev_b32_e32 v54, 16, v199
	v_lshlrev_b32_e32 v55, 16, v200
	v_add_f32_e32 v41, 1.0, v41
	v_rcp_f32_e32 v50, v41
	v_mul_f32_e32 v41, 0xbfb8aa3b, v47
	v_exp_f32_e32 v41, v41
	v_pk_mov_b32 v[52:53], v[52:53], v[54:55] op_sel:[1,0]
	v_and_or_b32 v37, v61, s39, v60
	v_and_or_b32 v38, v45, s39, v34
	v_add_f32_e32 v41, 1.0, v41
	v_rcp_f32_e32 v59, v41
	v_mul_f32_e32 v41, 0xbfb8aa3b, v49
	v_exp_f32_e32 v41, v41
	v_or_b32_sdwa v34, v40, v42 dst_sel:DWORD dst_unused:UNUSED_PAD src0_sel:WORD_1 src1_sel:DWORD
	v_pk_mul_f32 v[46:47], v[46:47], v[58:59]
	v_pk_fma_f32 v[58:59], v[84:85], v[52:53], 0 op_sel_hi:[1,1,0]
	v_add_f32_e32 v41, 1.0, v41
	v_rcp_f32_e32 v51, v41
	v_and_b32_e32 v42, 0xffff0000, v195
	ds_write_b128 v62, v[36:39] offset:34816
	ds_write_b128 v62, v[32:35] offset:34960
	v_and_b32_e32 v44, 0xffff0000, v191
	v_pk_mul_f32 v[48:49], v[48:49], v[50:51]
	v_lshlrev_b32_e32 v50, 16, v201
	v_lshlrev_b32_e32 v51, 16, v202
	v_pk_mov_b32 v[60:61], v[56:57], v[50:51] op_sel:[1,0]
	v_pk_fma_f32 v[56:57], v[84:85], v[56:57], 0 op_sel_hi:[1,1,0]
	v_pk_fma_f32 v[58:59], v[86:87], v[60:61], v[58:59]
	v_pk_fma_f32 v[52:53], v[86:87], v[52:53], v[56:57]
	v_pk_fma_f32 v[58:59], v[88:89], v[54:55], v[58:59]
	v_pk_fma_f32 v[52:53], v[88:89], v[60:61], v[52:53]
	v_pk_fma_f32 v[50:51], v[90:91], v[50:51], v[58:59]
	v_pk_fma_f32 v[52:53], v[90:91], v[54:55], v[52:53]
	v_mul_f32_e32 v41, 0xbfb8aa3b, v51
	v_exp_f32_e32 v41, v41
	s_nop 0
	s_nop 0
	s_nop 0
	v_add_f32_e32 v41, 1.0, v41
	v_rcp_f32_e32 v59, v41
	v_mul_f32_e32 v41, 0xbfb8aa3b, v52
	v_exp_f32_e32 v41, v41
	s_nop 0
	s_nop 0
	v_and_b32_e32 v36, 0xffff0000, v194
	v_add_f32_e32 v41, 1.0, v41
	v_rcp_f32_e32 v54, v41
	v_mul_f32_e32 v41, 0xbfb8aa3b, v50
	v_exp_f32_e32 v41, v41
	v_cvt_pk_bf16_f32 v47, v47, v49
	v_mov_b32_e32 v45, v42
	v_and_b32_e32 v40, 0xffff0000, v193
	v_add_f32_e32 v41, 1.0, v41
	v_rcp_f32_e32 v58, v41
	v_mul_f32_e32 v41, 0xbfb8aa3b, v53
	v_exp_f32_e32 v41, v41
	v_and_b32_e32 v32, 0xffff0000, v197
	v_pk_mul_f32 v[50:51], v[50:51], v[58:59]
	v_pk_fma_f32 v[44:45], v[100:101], v[44:45], 0 op_sel_hi:[1,1,0]
	v_add_f32_e32 v41, 1.0, v41
	v_rcp_f32_e32 v55, v41
	s_nop 0
	s_nop 0
	s_nop 0
	v_pk_mul_f32 v[52:53], v[52:53], v[54:55]
	v_cvt_pk_bf16_f32 v54, v48, v48
	v_bfe_u32 v48, v46, 16, 1
	v_add3_u32 v46, v46, v48, s68
	v_cvt_pk_bf16_f32 v49, v53, v51
	v_mov_b32_e32 v41, v36
	v_cvt_pk_bf16_f32 v48, v52, v50
	v_mov_b32_e32 v43, v32
	v_pk_fma_f32 v[44:45], v[102:103], v[40:41], v[44:45]
	v_and_b32_e32 v37, 0xffff0000, v196
	v_pk_fma_f32 v[44:45], v[104:105], v[42:43], v[44:45]
	v_pk_fma_f32 v[40:41], v[100:101], v[40:41], 0 op_sel_hi:[1,1,0]
	v_pk_fma_f32 v[44:45], v[106:107], v[36:37], v[44:45]
	v_pk_fma_f32 v[40:41], v[102:103], v[42:43], v[40:41]
	v_mul_f32_e32 v43, 0xbfb8aa3b, v45
	v_exp_f32_e32 v43, v43
	v_and_b32_e32 v33, 0xffff0000, v198
	v_pk_fma_f32 v[40:41], v[104:105], v[36:37], v[40:41]
	v_mul_f32_e32 v50, 0xbfb8aa3b, v44
	v_pk_fma_f32 v[40:41], v[106:107], v[32:33], v[40:41]
	v_add_f32_e32 v43, 1.0, v43
	v_mul_f32_e32 v42, 0xbfb8aa3b, v40
	v_rcp_f32_e32 v51, v43
	v_mul_f32_e32 v43, 0xbfb8aa3b, v41
	v_exp_f32_e32 v50, v50
	v_exp_f32_e32 v42, v42
	v_exp_f32_e32 v43, v43
	v_and_b32_e32 v35, 0xffff0000, v200
	v_add_f32_e32 v50, 1.0, v50
	v_add_f32_e32 v42, 1.0, v42
	v_add_f32_e32 v43, 1.0, v43
	v_rcp_f32_e32 v50, v50
	v_rcp_f32_e32 v42, v42
	v_rcp_f32_e32 v43, v43
	v_and_b32_e32 v34, 0xffff0000, v199
	v_and_b32_e32 v39, 0xffff0000, v202
	v_and_b32_e32 v38, 0xffff0000, v201
	v_pk_mov_b32 v[36:37], v[36:37], v[34:35] op_sel:[1,0]
	v_pk_mul_f32 v[44:45], v[44:45], v[50:51]
	v_pk_mul_f32 v[40:41], v[40:41], v[42:43]
	v_pk_fma_f32 v[42:43], v[100:101], v[36:37], 0 op_sel_hi:[1,1,0]
	v_pk_mov_b32 v[50:51], v[32:33], v[38:39] op_sel:[1,0]
	v_pk_fma_f32 v[32:33], v[100:101], v[32:33], 0 op_sel_hi:[1,1,0]
	v_pk_fma_f32 v[42:43], v[102:103], v[50:51], v[42:43]
	v_pk_fma_f32 v[32:33], v[102:103], v[36:37], v[32:33]
	v_pk_fma_f32 v[42:43], v[104:105], v[34:35], v[42:43]
	v_pk_fma_f32 v[32:33], v[104:105], v[50:51], v[32:33]
	v_pk_fma_f32 v[38:39], v[106:107], v[38:39], v[42:43]
	v_pk_fma_f32 v[32:33], v[106:107], v[34:35], v[32:33]
	v_mul_f32_e32 v42, 0xbfb8aa3b, v39
	v_mul_f32_e32 v35, 0xbfb8aa3b, v38
	v_exp_f32_e32 v42, v42
	v_exp_f32_e32 v35, v35
	v_mul_f32_e32 v34, 0xbfb8aa3b, v32
	v_exp_f32_e32 v34, v34
	v_add_f32_e32 v42, 1.0, v42
	v_add_f32_e32 v35, 1.0, v35
	v_rcp_f32_e32 v43, v42
	v_rcp_f32_e32 v42, v35
	v_mul_f32_e32 v35, 0xbfb8aa3b, v33
	v_exp_f32_e32 v35, v35
	v_add_f32_e32 v34, 1.0, v34
	v_rcp_f32_e32 v34, v34
	v_pk_mul_f32 v[36:37], v[38:39], v[42:43]
	v_add_f32_e32 v35, 1.0, v35
	v_rcp_f32_e32 v35, v35
	s_nop 0
	s_nop 0
	v_cvt_pk_bf16_f32 v38, v41, v41
	v_pk_mul_f32 v[32:33], v[32:33], v[34:35]
	v_bfe_u32 v35, v36, 16, 1
	v_add3_u32 v36, v36, v35, s68
	v_cvt_pk_bf16_f32 v34, v37, v37
	v_cvt_pk_bf16_f32 v37, v40, v40
	v_bfe_u32 v41, v45, 16, 1
	v_lshrrev_b32_e32 v46, 16, v46
	v_cvt_pk_bf16_f32 v33, v33, v33
	v_cvt_pk_bf16_f32 v32, v32, v32
	v_add3_u32 v35, v45, v41, s68
	v_cvt_pk_bf16_f32 v39, v44, v44
	v_and_or_b32 v46, v54, s39, v46
	v_lshrrev_b32_e32 v32, 16, v32
	v_lshrrev_b32_e32 v33, 16, v33
	v_lshrrev_b32_e32 v39, 16, v39
	v_lshrrev_b32_e32 v40, 16, v35
	v_lshlrev_b32_e32 v60, 1, v67
	v_and_or_b32 v35, v34, s39, v33
	v_and_or_b32 v34, v36, s39, v32
	v_and_or_b32 v33, v38, s39, v40
	v_and_or_b32 v32, v37, s39, v39
	ds_write_b128 v62, v[46:49] offset:53248
	ds_write_b128 v62, v[32:35] offset:53392
	s_cbranch_scc1 .LBB0_425
; DI void gdn_unit(const Params& P, bf16_t* proj, const float* gb, int b, int h, LAS unsigned char* lds) {
;     ...
;         if (n + 1 < 32) {
; #pragma unroll
;             for (int w = 0; w < 3; ++w) {
;                 const bf16_t* rbase = proj + (size_t)(t0 + 64 + wave * 8 - 3) * PJ1 + w * 1024 + h * 128;
; #pragma unroll
;                 for (int i = 0; i < 11; ++i) rawq[w][i] = *(const unsigned*)(rbase + i * PJ1 + 2 * lane);
;             }
;             gbl = gb[(size_t)(t0 + 64 + lane) * 16 + h]; gai = gb[(size_t)(t0 + 64 + lane) * 16 + 8 + h];
	s_add_i32 s0, s41, s42
	s_add_i32 s0, s0, -3
	s_ashr_i32 s1, s0, 31
	s_lshl_b64 s[0:1], s[0:1], 13
	s_add_u32 s0, s43, s0
	s_addc_u32 s1, s44, s1
	v_ashrrev_i32_e32 v61, 31, v60
	v_lshl_add_u64 v[32:33], v[60:61], 1, s[0:1]
	s_movk_i32 s0, 0x2000
	v_add_co_u32_e32 v34, vcc, s0, v32
	s_movk_i32 s0, 0x3000
	s_nop 0
	v_addc_co_u32_e32 v35, vcc, 0, v33, vcc
	v_add_co_u32_e32 v36, vcc, s0, v32
	s_movk_i32 s0, 0x4000
	s_nop 0
	v_addc_co_u32_e32 v37, vcc, 0, v33, vcc
	v_add_co_u32_e32 v38, vcc, s0, v32
	s_movk_i32 s0, 0x5000
	s_nop 0
	v_addc_co_u32_e32 v39, vcc, 0, v33, vcc
	v_add_co_u32_e32 v40, vcc, s0, v32
	s_movk_i32 s0, 0x6000
	s_nop 0
	v_addc_co_u32_e32 v41, vcc, 0, v33, vcc
	v_add_co_u32_e32 v42, vcc, s0, v32
	s_movk_i32 s0, 0x7000
	s_nop 0
	v_addc_co_u32_e32 v43, vcc, 0, v33, vcc
	v_add_co_u32_e32 v44, vcc, s0, v32
	s_mov_b32 s0, 0x8000
	s_nop 0
	v_addc_co_u32_e32 v45, vcc, 0, v33, vcc
	v_add_co_u32_e32 v46, vcc, s0, v32
	s_mov_b32 s0, 0x9000
	s_nop 0
	v_addc_co_u32_e32 v47, vcc, 0, v33, vcc
	v_add_co_u32_e32 v48, vcc, s0, v32
	s_mov_b32 s0, 0xa000
	s_nop 0
	v_addc_co_u32_e32 v49, vcc, 0, v33, vcc
	v_add_co_u32_e32 v50, vcc, s0, v32
	s_mov_b32 s0, 0xb000
	s_nop 0
	v_addc_co_u32_e32 v51, vcc, 0, v33, vcc
	v_add_co_u32_e32 v52, vcc, s0, v32
	s_mov_b32 s0, 0xc000
	s_nop 0
	v_addc_co_u32_e32 v53, vcc, 0, v33, vcc
	v_add_co_u32_e32 v54, vcc, s0, v32
	s_mov_b32 s0, 0xd000
	s_nop 0
	v_addc_co_u32_e32 v55, vcc, 0, v33, vcc
	v_add_co_u32_e32 v56, vcc, s0, v32
	s_mov_b32 s0, 0xe000
	s_nop 0
	v_addc_co_u32_e32 v57, vcc, 0, v33, vcc
	v_add_co_u32_e32 v58, vcc, s0, v32
	s_mov_b32 s0, 0xf000
	s_nop 0
	v_addc_co_u32_e32 v59, vcc, 0, v33, vcc
	v_add_co_u32_e32 v62, vcc, s0, v32
	s_mov_b32 s0, 0x10000
	s_nop 0
	v_addc_co_u32_e32 v63, vcc, 0, v33, vcc
	v_add_co_u32_e32 v64, vcc, s0, v32
	s_mov_b32 s0, 0x11000
	s_nop 0
	v_addc_co_u32_e32 v65, vcc, 0, v33, vcc
	v_add_co_u32_e32 v110, vcc, s0, v32
	s_mov_b32 s0, 0x12000
	s_nop 0
	v_addc_co_u32_e32 v111, vcc, 0, v33, vcc
	v_add_co_u32_e32 v112, vcc, s0, v32
	s_mov_b32 s0, 0x14000
	s_nop 0
	v_addc_co_u32_e32 v113, vcc, 0, v33, vcc
	v_add_co_u32_e32 v114, vcc, s0, v32
	s_movk_i32 s0, 0x1000
	s_nop 0
	v_addc_co_u32_e32 v115, vcc, 0, v33, vcc
	global_load_dword v136, v[32:33], off
	global_load_dword v177, v[32:33], off offset:2048
	global_load_dword v181, v[34:35], off offset:2048
	global_load_dword v180, v[38:39], off offset:2048
	global_load_dword v184, v[42:43], off offset:2048
	global_load_dword v183, v[46:47], off offset:2048
	global_load_dword v186, v[50:51], off offset:2048
	global_load_dword v185, v[54:55], off offset:2048
	v_add_co_u32_e32 v34, vcc, s0, v32
	s_nop 1
	v_addc_co_u32_e32 v35, vcc, 0, v33, vcc
	v_add_co_u32_e32 v38, vcc, 0x13000, v32
	s_nop 1
	v_addc_co_u32_e32 v39, vcc, 0, v33, vcc
	global_load_dword v178, v[112:113], off
	global_load_dword v182, v[114:115], off
	global_load_dword v187, v[58:59], off offset:2048
	global_load_dword v189, v[114:115], off offset:2048
	global_load_dword v191, v[34:35], off
	global_load_dword v200, v[38:39], off
	global_load_dword v190, v[112:113], off offset:2048
	global_load_dword v188, v[64:65], off offset:2048
	global_load_dword v159, v[48:49], off offset:-4096
	global_load_dword v158, v[52:53], off offset:-4096
	global_load_dword v176, v[56:57], off offset:-4096
	global_load_dword v161, v[62:63], off offset:-4096
	global_load_dword v198, v[56:57], off
	global_load_dword v196, v[52:53], off
	global_load_dword v197, v[48:49], off
	global_load_dword v194, v[44:45], off
	global_load_dword v179, v[110:111], off offset:-4096
	global_load_dword v201, v[110:111], off
	global_load_dword v199, v[62:63], off
	v_add_u32_e32 v34, s42, v67
	v_ashrrev_i32_e32 v35, 31, v34
	v_add_co_u32_e32 v32, vcc, 0x15000, v32
	v_lshlrev_b64 v[34:35], 6, v[34:35]
	s_nop 0
	v_addc_co_u32_e32 v33, vcc, 0, v33, vcc
	v_lshl_add_u64 v[34:35], s[6:7], 0, v[34:35]
	global_load_dword v157, v[36:37], off offset:-4096
	global_load_dword v156, v[40:41], off offset:-4096
	global_load_dword v160, v[44:45], off offset:-4096
	global_load_dword v195, v[40:41], off
	global_load_dword v193, v[36:37], off
	global_load_dword v202, v[32:33], off
	global_load_dword v203, v[34:35], off
	global_load_dword v204, v[34:35], off offset:32
